# baseline (speedup 1.0000x reference)
; template <int NS, bool LORA, int mat> ...
;     ...
;   const int ch = 64 * head + lane;
;   const float kk_c = p.k_k[ch], ka_c = p.k_a[ch], rk_c = p.r_k[ch];
;   const float mu_r = p.mu_shift[ch], mu_k = p.mu_shift[1024 + ch], mu_v = p.mu_shift[2048 + ch];
;   uint4 la[2][6];
;   u16 rv[2][NS][9];
.LBB0_1118:
	s_lshl_b32 s4, s89, 7
	s_add_i32 s4, s4, s60
	s_lshr_b32 s10, s4, 5
	s_lshl_b64 s[4:5], s[10:11], 11
	s_waitcnt vmcnt(17)
	v_mov_b32 v144, v146
	s_add_u32 s90, s4, 0x4000
	v_ashrrev_i32_e32 v7, 6, v144
	s_waitcnt vmcnt(13)
	v_and_b32_e32 v149, 63, v144
	v_cmp_lt_i32_e32 vcc, 3, v7
	s_and_saveexec_b64 s[4:5], vcc
	s_xor_b64 s[52:53], exec, s[4:5]
	s_cbranch_execz .LBB0_1213
	v_cmp_lt_i32_e32 vcc, 4, v7
	s_and_saveexec_b64 s[4:5], vcc
	s_xor_b64 s[54:55], exec, s[4:5]
	s_cbranch_execz .LBB0_1188
	v_cmp_ne_u32_e32 vcc, 5, v7
	s_and_saveexec_b64 s[4:5], vcc
	s_xor_b64 s[6:7], exec, s[4:5]
	s_cbranch_execz .LBB0_1155
	v_readfirstlane_b32 s4, v7
	v_and_b32_e32 v48, 7, v149
	v_lshrrev_b32_e32 v49, 3, v149
	s_sub_i32 s4, s4, 6
	s_lshl_b32 s4, s4, 3
	v_add_u32_e32 v50, s4, v49
	v_lshl_add_u32 v51, v48, 3, s62
	s_mul_i32 s4, s90, 0x1c00
	v_lshlrev_b32_e32 v52, 1, v51
	v_add_u32_e32 v52, 0x800, v52
	v_add_u32_e32 v52, s4, v52
	v_lshlrev_b32_e32 v51, 2, v51
	v_mov_b32_e32 v53, 0x1c00
	v_mov_b32_e32 v58, 0x7ff
	v_mov_b32_e32 v59, -16
	v_cndmask_b32_e64 v59, v59, 16, s[0:1]
	v_add_u32_e32 v205, 0x1000, v51
	v_add_u32_e32 v206, 0x2000, v51
	global_load_dwordx4 v[0:3], v51, s[50:51]
	global_load_dwordx4 v[4:7], v51, s[50:51] offset:16
	global_load_dwordx4 v[8:11], v51, s[16:17]
	global_load_dwordx4 v[12:15], v51, s[16:17] offset:16
	global_load_dwordx4 v[16:19], v51, s[18:19]
	global_load_dwordx4 v[20:23], v51, s[18:19] offset:16
	global_load_dwordx4 v[24:27], v51, s[38:39]
	global_load_dwordx4 v[28:31], v51, s[38:39] offset:16
	global_load_dwordx4 v[32:35], v205, s[38:39]
	global_load_dwordx4 v[36:39], v205, s[38:39] offset:16
	global_load_dwordx4 v[40:43], v206, s[38:39]
	global_load_dwordx4 v[44:47], v206, s[38:39] offset:16
	v_mul_u32_u24_e32 v54, 0x500, v50
	v_lshlrev_b32_e32 v55, 8, v50
	v_lshl_add_u32 v54, v48, 5, v54
	v_lshl_add_u32 v55, v48, 5, v55
	v_add_u32_e32 v54, 0x5000, v54
	v_add_u32_e32 v55, 0x3000, v55
	v_sub_u32_e32 v205, v58, v50
	v_cndmask_b32_e64 v56, v205, v50, s[0:1]
	v_cmp_eq_u32_e64 s[8:9], 0, v48
	s_waitcnt vmcnt(0)
	v_cmp_lt_i32_e64 s[4:5], 0, v56
	v_cmp_gt_i32_e64 s[58:59], v58, v56
	v_mad_u32_u24 v205, v56, v53, v52
	s_nop 0
	v_cndmask_b32_e64 v206, 0, v53, s[4:5]
	v_cndmask_b32_e64 v207, 0, v53, s[58:59]
	v_cndmask_b32_e64 v60, 0, 1.0, s[4:5]
	v_cndmask_b32_e64 v61, 0, 1.0, s[58:59]
	v_sub_u32_e32 v206, v205, v206
	v_add_u32_e32 v207, v205, v207
	global_load_dwordx4 v[64:67], v205, s[72:73] offset:-2048
	global_load_dwordx4 v[68:71], v205, s[72:73]
	global_load_dwordx4 v[72:75], v205, s[72:73] offset:2048
	global_load_dwordx4 v[76:79], v206, s[72:73] offset:-2048
	global_load_dwordx4 v[80:83], v206, s[72:73]
	global_load_dwordx4 v[84:87], v206, s[72:73] offset:2048
	global_load_dwordx4 v[88:91], v207, s[72:73] offset:-2048
	global_load_dwordx4 v[92:95], v207, s[72:73]
	global_load_dwordx4 v[96:99], v207, s[72:73] offset:2048
	v_add_u32_e32 v57, v59, v56
	v_cmp_lt_i32_e64 s[4:5], 0, v57
	v_cmp_gt_i32_e64 s[58:59], v58, v57
	v_mad_u32_u24 v205, v57, v53, v52
	s_nop 0
	v_cndmask_b32_e64 v206, 0, v53, s[4:5]
	v_cndmask_b32_e64 v207, 0, v53, s[58:59]
	v_cndmask_b32_e64 v62, 0, 1.0, s[4:5]
	v_cndmask_b32_e64 v63, 0, 1.0, s[58:59]
	v_sub_u32_e32 v206, v205, v206
	v_add_u32_e32 v207, v205, v207
	global_load_dwordx4 v[100:103], v205, s[72:73] offset:-2048
	global_load_dwordx4 v[104:107], v205, s[72:73]
	global_load_dwordx4 v[108:111], v205, s[72:73] offset:2048
	global_load_dwordx4 v[112:115], v206, s[72:73] offset:-2048
	global_load_dwordx4 v[116:119], v206, s[72:73]
	global_load_dwordx4 v[120:123], v206, s[72:73] offset:2048
	global_load_dwordx4 v[124:127], v207, s[72:73] offset:-2048
	global_load_dwordx4 v[128:131], v207, s[72:73]
	global_load_dwordx4 v[132:135], v207, s[72:73] offset:2048
	s_mov_b32 s10, 3
	s_waitcnt lgkmcnt(0)
	s_barrier
	ds_read_b128 v[184:187], v55 offset:0
	ds_read_b128 v[188:191], v55 offset:16
	s_waitcnt vmcnt(9)
	v_lshlrev_b32_e32 v136, 16, v64
	v_lshlrev_b32_e32 v192, 16, v76
	v_lshlrev_b32_e32 v193, 16, v88
	v_mul_f32_e32 v193, v61, v193
	v_fmac_f32_e32 v193, v60, v192
	v_fma_f32 v192, v193, 0.5, -v136
	v_fmac_f32_e32 v136, v24, v192
	v_and_b32_e32 v137, 0xffff0000, v64
	v_and_b32_e32 v192, 0xffff0000, v76
	v_and_b32_e32 v193, 0xffff0000, v88
	v_mul_f32_e32 v193, v61, v193
	v_fmac_f32_e32 v193, v60, v192
	v_fma_f32 v192, v193, 0.5, -v137
	v_fmac_f32_e32 v137, v25, v192
	v_lshlrev_b32_e32 v138, 16, v65
	v_lshlrev_b32_e32 v192, 16, v77
	v_lshlrev_b32_e32 v193, 16, v89
	v_mul_f32_e32 v193, v61, v193
	v_fmac_f32_e32 v193, v60, v192
	v_fma_f32 v192, v193, 0.5, -v138
	v_fmac_f32_e32 v138, v26, v192
	v_and_b32_e32 v139, 0xffff0000, v65
	v_and_b32_e32 v192, 0xffff0000, v77
	v_and_b32_e32 v193, 0xffff0000, v89
	v_mul_f32_e32 v193, v61, v193
	v_fmac_f32_e32 v193, v60, v192
	v_fma_f32 v192, v193, 0.5, -v139
	v_fmac_f32_e32 v139, v27, v192
	v_lshlrev_b32_e32 v140, 16, v66
	v_lshlrev_b32_e32 v192, 16, v78
	v_lshlrev_b32_e32 v193, 16, v90
	v_mul_f32_e32 v193, v61, v193
	v_fmac_f32_e32 v193, v60, v192
	v_fma_f32 v192, v193, 0.5, -v140
	v_fmac_f32_e32 v140, v28, v192
	v_and_b32_e32 v141, 0xffff0000, v66
	v_and_b32_e32 v192, 0xffff0000, v78
	v_and_b32_e32 v193, 0xffff0000, v90
	v_mul_f32_e32 v193, v61, v193
	v_fmac_f32_e32 v193, v60, v192
	v_fma_f32 v192, v193, 0.5, -v141
	v_fmac_f32_e32 v141, v29, v192
	v_lshlrev_b32_e32 v142, 16, v67
	v_lshlrev_b32_e32 v192, 16, v79
	v_lshlrev_b32_e32 v193, 16, v91
	v_mul_f32_e32 v193, v61, v193
	v_fmac_f32_e32 v193, v60, v192
	v_fma_f32 v192, v193, 0.5, -v142
	v_fmac_f32_e32 v142, v30, v192
	v_and_b32_e32 v143, 0xffff0000, v67
	v_and_b32_e32 v192, 0xffff0000, v79
	v_and_b32_e32 v193, 0xffff0000, v91
	v_mul_f32_e32 v193, v61, v193
	v_fmac_f32_e32 v193, v60, v192
	v_fma_f32 v192, v193, 0.5, -v143
	v_fmac_f32_e32 v143, v31, v192
	v_lshlrev_b32_e32 v208, 16, v68
	v_lshlrev_b32_e32 v192, 16, v80
	v_lshlrev_b32_e32 v193, 16, v92
	v_mul_f32_e32 v193, v61, v193
	v_fmac_f32_e32 v193, v60, v192
	v_fma_f32 v192, v193, 0.5, -v208
	v_fmac_f32_e32 v208, v32, v192
	v_and_b32_e32 v209, 0xffff0000, v68
	v_and_b32_e32 v192, 0xffff0000, v80
	v_and_b32_e32 v193, 0xffff0000, v92
	v_mul_f32_e32 v193, v61, v193
	v_fmac_f32_e32 v193, v60, v192
	v_fma_f32 v192, v193, 0.5, -v209
	v_fmac_f32_e32 v209, v33, v192
	v_lshlrev_b32_e32 v210, 16, v69
	v_lshlrev_b32_e32 v192, 16, v81
	v_lshlrev_b32_e32 v193, 16, v93
	v_mul_f32_e32 v193, v61, v193
	v_fmac_f32_e32 v193, v60, v192
	v_fma_f32 v192, v193, 0.5, -v210
	v_fmac_f32_e32 v210, v34, v192
	v_and_b32_e32 v211, 0xffff0000, v69
	v_and_b32_e32 v192, 0xffff0000, v81
	v_and_b32_e32 v193, 0xffff0000, v93
	v_mul_f32_e32 v193, v61, v193
	v_fmac_f32_e32 v193, v60, v192
	v_fma_f32 v192, v193, 0.5, -v211
	v_fmac_f32_e32 v211, v35, v192
	v_lshlrev_b32_e32 v212, 16, v70
	v_lshlrev_b32_e32 v192, 16, v82
	v_lshlrev_b32_e32 v193, 16, v94
	v_mul_f32_e32 v193, v61, v193
	v_fmac_f32_e32 v193, v60, v192
	v_fma_f32 v192, v193, 0.5, -v212
	v_fmac_f32_e32 v212, v36, v192
	v_and_b32_e32 v213, 0xffff0000, v70
	v_and_b32_e32 v192, 0xffff0000, v82
	v_and_b32_e32 v193, 0xffff0000, v94
	v_mul_f32_e32 v193, v61, v193
	v_fmac_f32_e32 v193, v60, v192
	v_fma_f32 v192, v193, 0.5, -v213
	v_fmac_f32_e32 v213, v37, v192
	v_lshlrev_b32_e32 v214, 16, v71
	v_lshlrev_b32_e32 v192, 16, v83
	v_lshlrev_b32_e32 v193, 16, v95
	v_mul_f32_e32 v193, v61, v193
	v_fmac_f32_e32 v193, v60, v192
	v_fma_f32 v192, v193, 0.5, -v214
	v_fmac_f32_e32 v214, v38, v192
	v_and_b32_e32 v215, 0xffff0000, v71
	v_and_b32_e32 v192, 0xffff0000, v83
	v_and_b32_e32 v193, 0xffff0000, v95
	v_mul_f32_e32 v193, v61, v193
	v_fmac_f32_e32 v193, v60, v192
	v_fma_f32 v192, v193, 0.5, -v215
	v_fmac_f32_e32 v215, v39, v192
	v_lshlrev_b32_e32 v152, 16, v72
	v_lshlrev_b32_e32 v192, 16, v84
	v_lshlrev_b32_e32 v193, 16, v96
	v_mul_f32_e32 v193, v61, v193
	v_fmac_f32_e32 v193, v60, v192
	v_fma_f32 v192, v193, 0.5, -v152
	v_fmac_f32_e32 v152, v40, v192
	v_and_b32_e32 v153, 0xffff0000, v72
	v_and_b32_e32 v192, 0xffff0000, v84
	v_and_b32_e32 v193, 0xffff0000, v96
	v_mul_f32_e32 v193, v61, v193
	v_fmac_f32_e32 v193, v60, v192
	v_fma_f32 v192, v193, 0.5, -v153
	v_fmac_f32_e32 v153, v41, v192
	v_lshlrev_b32_e32 v154, 16, v73
	v_lshlrev_b32_e32 v192, 16, v85
	v_lshlrev_b32_e32 v193, 16, v97
	v_mul_f32_e32 v193, v61, v193
	v_fmac_f32_e32 v193, v60, v192
	v_fma_f32 v192, v193, 0.5, -v154
	v_fmac_f32_e32 v154, v42, v192
	v_and_b32_e32 v155, 0xffff0000, v73
	v_and_b32_e32 v192, 0xffff0000, v85
	v_and_b32_e32 v193, 0xffff0000, v97
	v_mul_f32_e32 v193, v61, v193
	v_fmac_f32_e32 v193, v60, v192
	v_fma_f32 v192, v193, 0.5, -v155
	v_fmac_f32_e32 v155, v43, v192
	v_lshlrev_b32_e32 v156, 16, v74
	v_lshlrev_b32_e32 v192, 16, v86
	v_lshlrev_b32_e32 v193, 16, v98
	v_mul_f32_e32 v193, v61, v193
	v_fmac_f32_e32 v193, v60, v192
	v_fma_f32 v192, v193, 0.5, -v156
	v_fmac_f32_e32 v156, v44, v192
	v_and_b32_e32 v157, 0xffff0000, v74
	v_and_b32_e32 v192, 0xffff0000, v86
	v_and_b32_e32 v193, 0xffff0000, v98
	v_mul_f32_e32 v193, v61, v193
	v_fmac_f32_e32 v193, v60, v192
	v_fma_f32 v192, v193, 0.5, -v157
	v_fmac_f32_e32 v157, v45, v192
	v_lshlrev_b32_e32 v158, 16, v75
	v_lshlrev_b32_e32 v192, 16, v87
	v_lshlrev_b32_e32 v193, 16, v99
	v_mul_f32_e32 v193, v61, v193
	v_fmac_f32_e32 v193, v60, v192
	v_fma_f32 v192, v193, 0.5, -v158
	v_fmac_f32_e32 v158, v46, v192
	v_and_b32_e32 v159, 0xffff0000, v75
	v_and_b32_e32 v192, 0xffff0000, v87
	v_and_b32_e32 v193, 0xffff0000, v99
	v_mul_f32_e32 v193, v61, v193
	v_fmac_f32_e32 v193, v60, v192
	v_fma_f32 v192, v193, 0.5, -v159
	v_fmac_f32_e32 v159, v47, v192
	v_add_u32_e32 v57, v59, v56
	v_add_u32_e32 v57, v59, v57
	v_cmp_lt_i32_e64 s[4:5], 0, v57
	v_cmp_gt_i32_e64 s[58:59], v58, v57
	v_mad_u32_u24 v205, v57, v53, v52
	s_nop 0
	v_cndmask_b32_e64 v206, 0, v53, s[4:5]
	v_cndmask_b32_e64 v207, 0, v53, s[58:59]
	v_cndmask_b32_e64 v60, 0, 1.0, s[4:5]
	v_cndmask_b32_e64 v61, 0, 1.0, s[58:59]
	v_sub_u32_e32 v206, v205, v206
	v_add_u32_e32 v207, v205, v207
	global_load_dwordx4 v[64:67], v205, s[72:73] offset:-2048
	global_load_dwordx4 v[68:71], v205, s[72:73]
	global_load_dwordx4 v[72:75], v205, s[72:73] offset:2048
	global_load_dwordx4 v[76:79], v206, s[72:73] offset:-2048
	global_load_dwordx4 v[80:83], v206, s[72:73]
	global_load_dwordx4 v[84:87], v206, s[72:73] offset:2048
	global_load_dwordx4 v[88:91], v207, s[72:73] offset:-2048
	global_load_dwordx4 v[92:95], v207, s[72:73]
	global_load_dwordx4 v[96:99], v207, s[72:73] offset:2048
	v_mul_f32_e32 v160, v0, v208
	v_mul_f32_e32 v161, v1, v209
	v_mul_f32_e32 v162, v2, v210
	v_mul_f32_e32 v163, v3, v211
	v_mul_f32_e32 v164, v4, v212
	v_mul_f32_e32 v165, v5, v213
	v_mul_f32_e32 v166, v6, v214
	v_mul_f32_e32 v167, v7, v215
	v_mul_f32_e32 v200, v160, v160
	v_fmac_f32_e32 v200, v161, v161
	v_fmac_f32_e32 v200, v162, v162
	v_fmac_f32_e32 v200, v163, v163
	v_fmac_f32_e32 v200, v164, v164
	v_fmac_f32_e32 v200, v165, v165
	v_fmac_f32_e32 v200, v166, v166
	v_fmac_f32_e32 v200, v167, v167
	s_waitcnt lgkmcnt(0)
	v_add_f32_e32 v192, -1.0, v184
	v_fma_f32 v192, v8, v192, 1.0
	v_mul_f32_e32 v176, v208, v192
	v_add_f32_dpp v200, v200, v200 quad_perm:[1,0,3,2] row_mask:0xf bank_mask:0xf bound_ctrl:1
	v_add_f32_e32 v192, -1.0, v185
	v_fma_f32 v192, v9, v192, 1.0
	v_mul_f32_e32 v177, v209, v192
	v_add_f32_dpp v200, v200, v200 quad_perm:[2,3,0,1] row_mask:0xf bank_mask:0xf bound_ctrl:1
	v_add_f32_e32 v192, -1.0, v186
	v_fma_f32 v192, v10, v192, 1.0
	v_mul_f32_e32 v178, v210, v192
	v_add_f32_dpp v200, v200, v200 row_half_mirror row_mask:0xf bank_mask:0xf bound_ctrl:1
	v_add_f32_e32 v192, -1.0, v187
	v_fma_f32 v192, v11, v192, 1.0
	v_mul_f32_e32 v179, v211, v192
	v_add_f32_e32 v192, -1.0, v188
	v_fma_f32 v192, v12, v192, 1.0
	v_mul_f32_e32 v180, v212, v192
	v_add_f32_e32 v192, -1.0, v189
	v_fma_f32 v192, v13, v192, 1.0
	v_mul_f32_e32 v181, v213, v192
	v_add_f32_e32 v192, -1.0, v190
	v_fma_f32 v192, v14, v192, 1.0
	v_mul_f32_e32 v182, v214, v192
	v_add_f32_e32 v192, -1.0, v191
	v_fma_f32 v192, v15, v192, 1.0
	v_mul_f32_e32 v183, v215, v192
	v_max_f32_e32 v200, 0x179abe15, v200
	v_rsq_f32_e32 v201, v200
	v_mul_f32_e32 v192, v136, v176
	v_mul_f32_e32 v202, v16, v192
	v_mul_f32_e32 v160, v160, v201
	v_mul_f32_e32 v161, v161, v201
	v_mul_f32_e32 v162, v162, v201
	v_mul_f32_e32 v163, v163, v201
	v_mul_f32_e32 v164, v164, v201
	v_mul_f32_e32 v165, v165, v201
	v_mul_f32_e32 v166, v166, v201
	v_mul_f32_e32 v167, v167, v201
	v_mul_f32_e32 v168, v184, v160
	v_mul_f32_e32 v169, v185, v161
	v_mul_f32_e32 v170, v186, v162
	v_mul_f32_e32 v171, v187, v163
	v_mul_f32_e32 v172, v188, v164
	v_mul_f32_e32 v173, v189, v165
	v_mul_f32_e32 v174, v190, v166
	v_mul_f32_e32 v175, v191, v167
	ds_write_b128 v54, v[160:163] offset:0
	ds_write_b128 v54, v[164:167] offset:16
	ds_write_b128 v54, v[168:171] offset:256
	ds_write_b128 v54, v[172:175] offset:272
	v_mul_f32_e32 v192, v137, v177
	v_fmac_f32_e32 v202, v17, v192
	v_mul_f32_e32 v192, v138, v178
	v_fmac_f32_e32 v202, v18, v192
	v_mul_f32_e32 v192, v139, v179
	v_fmac_f32_e32 v202, v19, v192
	v_mul_f32_e32 v192, v140, v180
	v_fmac_f32_e32 v202, v20, v192
	v_mul_f32_e32 v192, v141, v181
	v_fmac_f32_e32 v202, v21, v192
	v_mul_f32_e32 v192, v142, v182
	v_fmac_f32_e32 v202, v22, v192
	v_mul_f32_e32 v192, v143, v183
	v_fmac_f32_e32 v202, v23, v192
	ds_write_b128 v54, v[176:179] offset:512
	ds_write_b128 v54, v[180:183] offset:528
	v_add_f32_dpp v202, v202, v202 quad_perm:[1,0,3,2] row_mask:0xf bank_mask:0xf bound_ctrl:1
	ds_write_b128 v54, v[136:139] offset:768
	ds_write_b128 v54, v[140:143] offset:784
	v_add_f32_dpp v202, v202, v202 quad_perm:[2,3,0,1] row_mask:0xf bank_mask:0xf bound_ctrl:1
	ds_write_b128 v54, v[152:155] offset:1024
	ds_write_b128 v54, v[156:159] offset:1040
	v_add_f32_dpp v202, v202, v202 row_half_mirror row_mask:0xf bank_mask:0xf bound_ctrl:1
	v_add_u32_e32 v205, s90, v56
	v_lshl_add_u32 v205, v205, 7, s64
	s_and_saveexec_b64 s[56:57], s[8:9]
	global_store_dword v205, v202, s[24:25]
	s_or_b64 exec, exec, s[56:57]
	v_add_u32_e32 v56, v59, v56
	s_waitcnt lgkmcnt(0)
	s_barrier
	ds_read_b128 v[184:187], v55 offset:4096
	ds_read_b128 v[188:191], v55 offset:4112
	s_waitcnt vmcnt(9)
	v_lshlrev_b32_e32 v136, 16, v100
	v_lshlrev_b32_e32 v192, 16, v112
	v_lshlrev_b32_e32 v193, 16, v124
	v_mul_f32_e32 v193, v63, v193
	v_fmac_f32_e32 v193, v62, v192
	v_fma_f32 v192, v193, 0.5, -v136
	v_fmac_f32_e32 v136, v24, v192
	v_and_b32_e32 v137, 0xffff0000, v100
	v_and_b32_e32 v192, 0xffff0000, v112
	v_and_b32_e32 v193, 0xffff0000, v124
	v_mul_f32_e32 v193, v63, v193
	v_fmac_f32_e32 v193, v62, v192
	v_fma_f32 v192, v193, 0.5, -v137
	v_fmac_f32_e32 v137, v25, v192
	v_lshlrev_b32_e32 v138, 16, v101
	v_lshlrev_b32_e32 v192, 16, v113
	v_lshlrev_b32_e32 v193, 16, v125
	v_mul_f32_e32 v193, v63, v193
	v_fmac_f32_e32 v193, v62, v192
	v_fma_f32 v192, v193, 0.5, -v138
	v_fmac_f32_e32 v138, v26, v192
	v_and_b32_e32 v139, 0xffff0000, v101
	v_and_b32_e32 v192, 0xffff0000, v113
	v_and_b32_e32 v193, 0xffff0000, v125
	v_mul_f32_e32 v193, v63, v193
	v_fmac_f32_e32 v193, v62, v192
	v_fma_f32 v192, v193, 0.5, -v139
	v_fmac_f32_e32 v139, v27, v192
	v_lshlrev_b32_e32 v140, 16, v102
	v_lshlrev_b32_e32 v192, 16, v114
	v_lshlrev_b32_e32 v193, 16, v126
	v_mul_f32_e32 v193, v63, v193
	v_fmac_f32_e32 v193, v62, v192
	v_fma_f32 v192, v193, 0.5, -v140
	v_fmac_f32_e32 v140, v28, v192
	v_and_b32_e32 v141, 0xffff0000, v102
	v_and_b32_e32 v192, 0xffff0000, v114
	v_and_b32_e32 v193, 0xffff0000, v126
	v_mul_f32_e32 v193, v63, v193
	v_fmac_f32_e32 v193, v62, v192
	v_fma_f32 v192, v193, 0.5, -v141
	v_fmac_f32_e32 v141, v29, v192
	v_lshlrev_b32_e32 v142, 16, v103
	v_lshlrev_b32_e32 v192, 16, v115
	v_lshlrev_b32_e32 v193, 16, v127
	v_mul_f32_e32 v193, v63, v193
	v_fmac_f32_e32 v193, v62, v192
	v_fma_f32 v192, v193, 0.5, -v142
	v_fmac_f32_e32 v142, v30, v192
	v_and_b32_e32 v143, 0xffff0000, v103
	v_and_b32_e32 v192, 0xffff0000, v115
	v_and_b32_e32 v193, 0xffff0000, v127
	v_mul_f32_e32 v193, v63, v193
	v_fmac_f32_e32 v193, v62, v192
	v_fma_f32 v192, v193, 0.5, -v143
	v_fmac_f32_e32 v143, v31, v192
	v_lshlrev_b32_e32 v208, 16, v104
	v_lshlrev_b32_e32 v192, 16, v116
	v_lshlrev_b32_e32 v193, 16, v128
	v_mul_f32_e32 v193, v63, v193
	v_fmac_f32_e32 v193, v62, v192
	v_fma_f32 v192, v193, 0.5, -v208
	v_fmac_f32_e32 v208, v32, v192
	v_and_b32_e32 v209, 0xffff0000, v104
	v_and_b32_e32 v192, 0xffff0000, v116
	v_and_b32_e32 v193, 0xffff0000, v128
	v_mul_f32_e32 v193, v63, v193
	v_fmac_f32_e32 v193, v62, v192
	v_fma_f32 v192, v193, 0.5, -v209
	v_fmac_f32_e32 v209, v33, v192
	v_lshlrev_b32_e32 v210, 16, v105
	v_lshlrev_b32_e32 v192, 16, v117
	v_lshlrev_b32_e32 v193, 16, v129
	v_mul_f32_e32 v193, v63, v193
	v_fmac_f32_e32 v193, v62, v192
	v_fma_f32 v192, v193, 0.5, -v210
	v_fmac_f32_e32 v210, v34, v192
	v_and_b32_e32 v211, 0xffff0000, v105
	v_and_b32_e32 v192, 0xffff0000, v117
	v_and_b32_e32 v193, 0xffff0000, v129
	v_mul_f32_e32 v193, v63, v193
	v_fmac_f32_e32 v193, v62, v192
	v_fma_f32 v192, v193, 0.5, -v211
	v_fmac_f32_e32 v211, v35, v192
	v_lshlrev_b32_e32 v212, 16, v106
	v_lshlrev_b32_e32 v192, 16, v118
	v_lshlrev_b32_e32 v193, 16, v130
	v_mul_f32_e32 v193, v63, v193
	v_fmac_f32_e32 v193, v62, v192
	v_fma_f32 v192, v193, 0.5, -v212
	v_fmac_f32_e32 v212, v36, v192
	v_and_b32_e32 v213, 0xffff0000, v106
	v_and_b32_e32 v192, 0xffff0000, v118
	v_and_b32_e32 v193, 0xffff0000, v130
	v_mul_f32_e32 v193, v63, v193
	v_fmac_f32_e32 v193, v62, v192
	v_fma_f32 v192, v193, 0.5, -v213
	v_fmac_f32_e32 v213, v37, v192
	v_lshlrev_b32_e32 v214, 16, v107
	v_lshlrev_b32_e32 v192, 16, v119
	v_lshlrev_b32_e32 v193, 16, v131
	v_mul_f32_e32 v193, v63, v193
	v_fmac_f32_e32 v193, v62, v192
	v_fma_f32 v192, v193, 0.5, -v214
	v_fmac_f32_e32 v214, v38, v192
	v_and_b32_e32 v215, 0xffff0000, v107
	v_and_b32_e32 v192, 0xffff0000, v119
	v_and_b32_e32 v193, 0xffff0000, v131
	v_mul_f32_e32 v193, v63, v193
	v_fmac_f32_e32 v193, v62, v192
	v_fma_f32 v192, v193, 0.5, -v215
	v_fmac_f32_e32 v215, v39, v192
	v_lshlrev_b32_e32 v152, 16, v108
	v_lshlrev_b32_e32 v192, 16, v120
	v_lshlrev_b32_e32 v193, 16, v132
	v_mul_f32_e32 v193, v63, v193
	v_fmac_f32_e32 v193, v62, v192
	v_fma_f32 v192, v193, 0.5, -v152
	v_fmac_f32_e32 v152, v40, v192
	v_and_b32_e32 v153, 0xffff0000, v108
	v_and_b32_e32 v192, 0xffff0000, v120
	v_and_b32_e32 v193, 0xffff0000, v132
	v_mul_f32_e32 v193, v63, v193
	v_fmac_f32_e32 v193, v62, v192
	v_fma_f32 v192, v193, 0.5, -v153
	v_fmac_f32_e32 v153, v41, v192
	v_lshlrev_b32_e32 v154, 16, v109
	v_lshlrev_b32_e32 v192, 16, v121
	v_lshlrev_b32_e32 v193, 16, v133
	v_mul_f32_e32 v193, v63, v193
	v_fmac_f32_e32 v193, v62, v192
	v_fma_f32 v192, v193, 0.5, -v154
	v_fmac_f32_e32 v154, v42, v192
	v_and_b32_e32 v155, 0xffff0000, v109
	v_and_b32_e32 v192, 0xffff0000, v121
	v_and_b32_e32 v193, 0xffff0000, v133
	v_mul_f32_e32 v193, v63, v193
	v_fmac_f32_e32 v193, v62, v192
	v_fma_f32 v192, v193, 0.5, -v155
	v_fmac_f32_e32 v155, v43, v192
	v_lshlrev_b32_e32 v156, 16, v110
	v_lshlrev_b32_e32 v192, 16, v122
	v_lshlrev_b32_e32 v193, 16, v134
	v_mul_f32_e32 v193, v63, v193
	v_fmac_f32_e32 v193, v62, v192
	v_fma_f32 v192, v193, 0.5, -v156
	v_fmac_f32_e32 v156, v44, v192
	v_and_b32_e32 v157, 0xffff0000, v110
	v_and_b32_e32 v192, 0xffff0000, v122
	v_and_b32_e32 v193, 0xffff0000, v134
	v_mul_f32_e32 v193, v63, v193
	v_fmac_f32_e32 v193, v62, v192
	v_fma_f32 v192, v193, 0.5, -v157
	v_fmac_f32_e32 v157, v45, v192
	v_lshlrev_b32_e32 v158, 16, v111
	v_lshlrev_b32_e32 v192, 16, v123
	v_lshlrev_b32_e32 v193, 16, v135
	v_mul_f32_e32 v193, v63, v193
	v_fmac_f32_e32 v193, v62, v192
	v_fma_f32 v192, v193, 0.5, -v158
	v_fmac_f32_e32 v158, v46, v192
	v_and_b32_e32 v159, 0xffff0000, v111
	v_and_b32_e32 v192, 0xffff0000, v123
	v_and_b32_e32 v193, 0xffff0000, v135
	v_mul_f32_e32 v193, v63, v193
	v_fmac_f32_e32 v193, v62, v192
	v_fma_f32 v192, v193, 0.5, -v159
	v_fmac_f32_e32 v159, v47, v192
	v_add_u32_e32 v57, v59, v56
	v_add_u32_e32 v57, v59, v57
	v_cmp_lt_i32_e64 s[4:5], 0, v57
	v_cmp_gt_i32_e64 s[58:59], v58, v57
	v_mad_u32_u24 v205, v57, v53, v52
	s_nop 0
	v_cndmask_b32_e64 v206, 0, v53, s[4:5]
	v_cndmask_b32_e64 v207, 0, v53, s[58:59]
	v_cndmask_b32_e64 v62, 0, 1.0, s[4:5]
	v_cndmask_b32_e64 v63, 0, 1.0, s[58:59]
	v_sub_u32_e32 v206, v205, v206
	v_add_u32_e32 v207, v205, v207
	global_load_dwordx4 v[100:103], v205, s[72:73] offset:-2048
	global_load_dwordx4 v[104:107], v205, s[72:73]
	global_load_dwordx4 v[108:111], v205, s[72:73] offset:2048
	global_load_dwordx4 v[112:115], v206, s[72:73] offset:-2048
	global_load_dwordx4 v[116:119], v206, s[72:73]
	global_load_dwordx4 v[120:123], v206, s[72:73] offset:2048
	global_load_dwordx4 v[124:127], v207, s[72:73] offset:-2048
	global_load_dwordx4 v[128:131], v207, s[72:73]
	global_load_dwordx4 v[132:135], v207, s[72:73] offset:2048
	v_mul_f32_e32 v160, v0, v208
	v_mul_f32_e32 v161, v1, v209
	v_mul_f32_e32 v162, v2, v210
	v_mul_f32_e32 v163, v3, v211
	v_mul_f32_e32 v164, v4, v212
	v_mul_f32_e32 v165, v5, v213
	v_mul_f32_e32 v166, v6, v214
	v_mul_f32_e32 v167, v7, v215
	v_mul_f32_e32 v200, v160, v160
	v_fmac_f32_e32 v200, v161, v161
	v_fmac_f32_e32 v200, v162, v162
	v_fmac_f32_e32 v200, v163, v163
	v_fmac_f32_e32 v200, v164, v164
	v_fmac_f32_e32 v200, v165, v165
	v_fmac_f32_e32 v200, v166, v166
	v_fmac_f32_e32 v200, v167, v167
	s_waitcnt lgkmcnt(0)
	v_add_f32_e32 v192, -1.0, v184
	v_fma_f32 v192, v8, v192, 1.0
	v_mul_f32_e32 v176, v208, v192
	v_add_f32_dpp v200, v200, v200 quad_perm:[1,0,3,2] row_mask:0xf bank_mask:0xf bound_ctrl:1
	v_add_f32_e32 v192, -1.0, v185
	v_fma_f32 v192, v9, v192, 1.0
	v_mul_f32_e32 v177, v209, v192
	v_add_f32_dpp v200, v200, v200 quad_perm:[2,3,0,1] row_mask:0xf bank_mask:0xf bound_ctrl:1
	v_add_f32_e32 v192, -1.0, v186
	v_fma_f32 v192, v10, v192, 1.0
	v_mul_f32_e32 v178, v210, v192
	v_add_f32_dpp v200, v200, v200 row_half_mirror row_mask:0xf bank_mask:0xf bound_ctrl:1
	v_add_f32_e32 v192, -1.0, v187
	v_fma_f32 v192, v11, v192, 1.0
	v_mul_f32_e32 v179, v211, v192
	v_add_f32_e32 v192, -1.0, v188
	v_fma_f32 v192, v12, v192, 1.0
	v_mul_f32_e32 v180, v212, v192
	v_add_f32_e32 v192, -1.0, v189
	v_fma_f32 v192, v13, v192, 1.0
	v_mul_f32_e32 v181, v213, v192
	v_add_f32_e32 v192, -1.0, v190
	v_fma_f32 v192, v14, v192, 1.0
	v_mul_f32_e32 v182, v214, v192
	v_add_f32_e32 v192, -1.0, v191
	v_fma_f32 v192, v15, v192, 1.0
	v_mul_f32_e32 v183, v215, v192
	v_max_f32_e32 v200, 0x179abe15, v200
	v_rsq_f32_e32 v201, v200
	v_mul_f32_e32 v192, v136, v176
	v_mul_f32_e32 v202, v16, v192
	v_mul_f32_e32 v160, v160, v201
	v_mul_f32_e32 v161, v161, v201
	v_mul_f32_e32 v162, v162, v201
	v_mul_f32_e32 v163, v163, v201
	v_mul_f32_e32 v164, v164, v201
	v_mul_f32_e32 v165, v165, v201
	v_mul_f32_e32 v166, v166, v201
	v_mul_f32_e32 v167, v167, v201
	v_mul_f32_e32 v168, v184, v160
	v_mul_f32_e32 v169, v185, v161
	v_mul_f32_e32 v170, v186, v162
	v_mul_f32_e32 v171, v187, v163
	v_mul_f32_e32 v172, v188, v164
	v_mul_f32_e32 v173, v189, v165
	v_mul_f32_e32 v174, v190, v166
	v_mul_f32_e32 v175, v191, v167
	ds_write_b128 v54, v[160:163] offset:20480
	ds_write_b128 v54, v[164:167] offset:20496
	ds_write_b128 v54, v[168:171] offset:20736
	ds_write_b128 v54, v[172:175] offset:20752
	v_mul_f32_e32 v192, v137, v177
	v_fmac_f32_e32 v202, v17, v192
	v_mul_f32_e32 v192, v138, v178
	v_fmac_f32_e32 v202, v18, v192
	v_mul_f32_e32 v192, v139, v179
	v_fmac_f32_e32 v202, v19, v192
	v_mul_f32_e32 v192, v140, v180
	v_fmac_f32_e32 v202, v20, v192
	v_mul_f32_e32 v192, v141, v181
	v_fmac_f32_e32 v202, v21, v192
	v_mul_f32_e32 v192, v142, v182
	v_fmac_f32_e32 v202, v22, v192
	v_mul_f32_e32 v192, v143, v183
	v_fmac_f32_e32 v202, v23, v192
	ds_write_b128 v54, v[176:179] offset:20992
	ds_write_b128 v54, v[180:183] offset:21008
	v_add_f32_dpp v202, v202, v202 quad_perm:[1,0,3,2] row_mask:0xf bank_mask:0xf bound_ctrl:1
	ds_write_b128 v54, v[136:139] offset:21248
	ds_write_b128 v54, v[140:143] offset:21264
	v_add_f32_dpp v202, v202, v202 quad_perm:[2,3,0,1] row_mask:0xf bank_mask:0xf bound_ctrl:1
	ds_write_b128 v54, v[152:155] offset:21504
	ds_write_b128 v54, v[156:159] offset:21520
	v_add_f32_dpp v202, v202, v202 row_half_mirror row_mask:0xf bank_mask:0xf bound_ctrl:1
	v_add_u32_e32 v205, s90, v56
	v_lshl_add_u32 v205, v205, 7, s64
	s_and_saveexec_b64 s[56:57], s[8:9]
	global_store_dword v205, v202, s[24:25]
	s_or_b64 exec, exec, s[56:57]
	v_add_u32_e32 v56, v59, v56
	s_waitcnt lgkmcnt(0)
	s_barrier
.Lmy_ks_loop:
	ds_read_b128 v[184:187], v55 offset:0
	ds_read_b128 v[188:191], v55 offset:16
	s_waitcnt vmcnt(9)
	v_lshlrev_b32_e32 v136, 16, v64
	v_lshlrev_b32_e32 v192, 16, v76
	v_lshlrev_b32_e32 v193, 16, v88
	v_add_f32_e32 v193, v193, v192
	v_fma_f32 v192, v193, 0.5, -v136
	v_fmac_f32_e32 v136, v24, v192
	v_and_b32_e32 v137, 0xffff0000, v64
	v_and_b32_e32 v192, 0xffff0000, v76
	v_and_b32_e32 v193, 0xffff0000, v88
	v_add_f32_e32 v193, v193, v192
	v_fma_f32 v192, v193, 0.5, -v137
	v_fmac_f32_e32 v137, v25, v192
	v_lshlrev_b32_e32 v138, 16, v65
	v_lshlrev_b32_e32 v192, 16, v77
	v_lshlrev_b32_e32 v193, 16, v89
	v_add_f32_e32 v193, v193, v192
	v_fma_f32 v192, v193, 0.5, -v138
	v_fmac_f32_e32 v138, v26, v192
	v_and_b32_e32 v139, 0xffff0000, v65
	v_and_b32_e32 v192, 0xffff0000, v77
	v_and_b32_e32 v193, 0xffff0000, v89
	v_add_f32_e32 v193, v193, v192
	v_fma_f32 v192, v193, 0.5, -v139
	v_fmac_f32_e32 v139, v27, v192
	v_lshlrev_b32_e32 v140, 16, v66
	v_lshlrev_b32_e32 v192, 16, v78
	v_lshlrev_b32_e32 v193, 16, v90
	v_add_f32_e32 v193, v193, v192
	v_fma_f32 v192, v193, 0.5, -v140
	v_fmac_f32_e32 v140, v28, v192
	v_and_b32_e32 v141, 0xffff0000, v66
	v_and_b32_e32 v192, 0xffff0000, v78
	v_and_b32_e32 v193, 0xffff0000, v90
	v_add_f32_e32 v193, v193, v192
	v_fma_f32 v192, v193, 0.5, -v141
	v_fmac_f32_e32 v141, v29, v192
	v_lshlrev_b32_e32 v142, 16, v67
	v_lshlrev_b32_e32 v192, 16, v79
	v_lshlrev_b32_e32 v193, 16, v91
	v_add_f32_e32 v193, v193, v192
	v_fma_f32 v192, v193, 0.5, -v142
	v_fmac_f32_e32 v142, v30, v192
	v_and_b32_e32 v143, 0xffff0000, v67
	v_and_b32_e32 v192, 0xffff0000, v79
	v_and_b32_e32 v193, 0xffff0000, v91
	v_add_f32_e32 v193, v193, v192
	v_fma_f32 v192, v193, 0.5, -v143
	v_fmac_f32_e32 v143, v31, v192
	v_lshlrev_b32_e32 v208, 16, v68
	v_lshlrev_b32_e32 v192, 16, v80
	v_lshlrev_b32_e32 v193, 16, v92
	v_add_f32_e32 v193, v193, v192
	v_fma_f32 v192, v193, 0.5, -v208
	v_fmac_f32_e32 v208, v32, v192
	v_and_b32_e32 v209, 0xffff0000, v68
	v_and_b32_e32 v192, 0xffff0000, v80
	v_and_b32_e32 v193, 0xffff0000, v92
	v_add_f32_e32 v193, v193, v192
	v_fma_f32 v192, v193, 0.5, -v209
	v_fmac_f32_e32 v209, v33, v192
	v_lshlrev_b32_e32 v210, 16, v69
	v_lshlrev_b32_e32 v192, 16, v81
	v_lshlrev_b32_e32 v193, 16, v93
	v_add_f32_e32 v193, v193, v192
	v_fma_f32 v192, v193, 0.5, -v210
	v_fmac_f32_e32 v210, v34, v192
	v_and_b32_e32 v211, 0xffff0000, v69
	v_and_b32_e32 v192, 0xffff0000, v81
	v_and_b32_e32 v193, 0xffff0000, v93
	v_add_f32_e32 v193, v193, v192
	v_fma_f32 v192, v193, 0.5, -v211
	v_fmac_f32_e32 v211, v35, v192
	v_lshlrev_b32_e32 v212, 16, v70
	v_lshlrev_b32_e32 v192, 16, v82
	v_lshlrev_b32_e32 v193, 16, v94
	v_add_f32_e32 v193, v193, v192
	v_fma_f32 v192, v193, 0.5, -v212
	v_fmac_f32_e32 v212, v36, v192
	v_and_b32_e32 v213, 0xffff0000, v70
	v_and_b32_e32 v192, 0xffff0000, v82
	v_and_b32_e32 v193, 0xffff0000, v94
	v_add_f32_e32 v193, v193, v192
	v_fma_f32 v192, v193, 0.5, -v213
	v_fmac_f32_e32 v213, v37, v192
	v_lshlrev_b32_e32 v214, 16, v71
	v_lshlrev_b32_e32 v192, 16, v83
	v_lshlrev_b32_e32 v193, 16, v95
	v_add_f32_e32 v193, v193, v192
	v_fma_f32 v192, v193, 0.5, -v214
	v_fmac_f32_e32 v214, v38, v192
	v_and_b32_e32 v215, 0xffff0000, v71
	v_and_b32_e32 v192, 0xffff0000, v83
	v_and_b32_e32 v193, 0xffff0000, v95
	v_add_f32_e32 v193, v193, v192
	v_fma_f32 v192, v193, 0.5, -v215
	v_fmac_f32_e32 v215, v39, v192
	v_lshlrev_b32_e32 v152, 16, v72
	v_lshlrev_b32_e32 v192, 16, v84
	v_lshlrev_b32_e32 v193, 16, v96
	v_add_f32_e32 v193, v193, v192
	v_fma_f32 v192, v193, 0.5, -v152
	v_fmac_f32_e32 v152, v40, v192
	v_and_b32_e32 v153, 0xffff0000, v72
	v_and_b32_e32 v192, 0xffff0000, v84
	v_and_b32_e32 v193, 0xffff0000, v96
	v_add_f32_e32 v193, v193, v192
	v_fma_f32 v192, v193, 0.5, -v153
	v_fmac_f32_e32 v153, v41, v192
	v_lshlrev_b32_e32 v154, 16, v73
	v_lshlrev_b32_e32 v192, 16, v85
	v_lshlrev_b32_e32 v193, 16, v97
	v_add_f32_e32 v193, v193, v192
	v_fma_f32 v192, v193, 0.5, -v154
	v_fmac_f32_e32 v154, v42, v192
	v_and_b32_e32 v155, 0xffff0000, v73
	v_and_b32_e32 v192, 0xffff0000, v85
	v_and_b32_e32 v193, 0xffff0000, v97
	v_add_f32_e32 v193, v193, v192
	v_fma_f32 v192, v193, 0.5, -v155
	v_fmac_f32_e32 v155, v43, v192
	v_lshlrev_b32_e32 v156, 16, v74
	v_lshlrev_b32_e32 v192, 16, v86
	v_lshlrev_b32_e32 v193, 16, v98
	v_add_f32_e32 v193, v193, v192
	v_fma_f32 v192, v193, 0.5, -v156
	v_fmac_f32_e32 v156, v44, v192
	v_and_b32_e32 v157, 0xffff0000, v74
	v_and_b32_e32 v192, 0xffff0000, v86
	v_and_b32_e32 v193, 0xffff0000, v98
	v_add_f32_e32 v193, v193, v192
	v_fma_f32 v192, v193, 0.5, -v157
	v_fmac_f32_e32 v157, v45, v192
	v_lshlrev_b32_e32 v158, 16, v75
	v_lshlrev_b32_e32 v192, 16, v87
	v_lshlrev_b32_e32 v193, 16, v99
	v_add_f32_e32 v193, v193, v192
	v_fma_f32 v192, v193, 0.5, -v158
	v_fmac_f32_e32 v158, v46, v192
	v_and_b32_e32 v159, 0xffff0000, v75
	v_and_b32_e32 v192, 0xffff0000, v87
	v_and_b32_e32 v193, 0xffff0000, v99
	v_add_f32_e32 v193, v193, v192
	v_fma_f32 v192, v193, 0.5, -v159
	v_fmac_f32_e32 v159, v47, v192
	v_add_u32_e32 v57, v59, v56
	v_add_u32_e32 v57, v59, v57
	v_cmp_lt_i32_e64 s[4:5], 0, v57
	v_cmp_gt_i32_e64 s[58:59], v58, v57
	v_mad_u32_u24 v205, v57, v53, v52
	s_nop 0
	v_cndmask_b32_e64 v206, 0, v53, s[4:5]
	v_cndmask_b32_e64 v207, 0, v53, s[58:59]
	v_cndmask_b32_e64 v60, 0, 1.0, s[4:5]
	v_cndmask_b32_e64 v61, 0, 1.0, s[58:59]
	v_sub_u32_e32 v206, v205, v206
	v_add_u32_e32 v207, v205, v207
	global_load_dwordx4 v[64:67], v205, s[72:73] offset:-2048
	global_load_dwordx4 v[68:71], v205, s[72:73]
	global_load_dwordx4 v[72:75], v205, s[72:73] offset:2048
	global_load_dwordx4 v[76:79], v206, s[72:73] offset:-2048
	global_load_dwordx4 v[80:83], v206, s[72:73]
	global_load_dwordx4 v[84:87], v206, s[72:73] offset:2048
	global_load_dwordx4 v[88:91], v207, s[72:73] offset:-2048
	global_load_dwordx4 v[92:95], v207, s[72:73]
	global_load_dwordx4 v[96:99], v207, s[72:73] offset:2048
	v_mul_f32_e32 v160, v0, v208
	v_mul_f32_e32 v161, v1, v209
	v_mul_f32_e32 v162, v2, v210
	v_mul_f32_e32 v163, v3, v211
	v_mul_f32_e32 v164, v4, v212
	v_mul_f32_e32 v165, v5, v213
	v_mul_f32_e32 v166, v6, v214
	v_mul_f32_e32 v167, v7, v215
	v_mul_f32_e32 v200, v160, v160
	v_fmac_f32_e32 v200, v161, v161
	v_fmac_f32_e32 v200, v162, v162
	v_fmac_f32_e32 v200, v163, v163
	v_fmac_f32_e32 v200, v164, v164
	v_fmac_f32_e32 v200, v165, v165
	v_fmac_f32_e32 v200, v166, v166
	v_fmac_f32_e32 v200, v167, v167
	s_waitcnt lgkmcnt(0)
	v_add_f32_e32 v192, -1.0, v184
	v_fma_f32 v192, v8, v192, 1.0
	v_mul_f32_e32 v176, v208, v192
	v_add_f32_dpp v200, v200, v200 quad_perm:[1,0,3,2] row_mask:0xf bank_mask:0xf bound_ctrl:1
	v_add_f32_e32 v192, -1.0, v185
	v_fma_f32 v192, v9, v192, 1.0
	v_mul_f32_e32 v177, v209, v192
	v_add_f32_dpp v200, v200, v200 quad_perm:[2,3,0,1] row_mask:0xf bank_mask:0xf bound_ctrl:1
	v_add_f32_e32 v192, -1.0, v186
	v_fma_f32 v192, v10, v192, 1.0
	v_mul_f32_e32 v178, v210, v192
	v_add_f32_dpp v200, v200, v200 row_half_mirror row_mask:0xf bank_mask:0xf bound_ctrl:1
	v_add_f32_e32 v192, -1.0, v187
	v_fma_f32 v192, v11, v192, 1.0
	v_mul_f32_e32 v179, v211, v192
	v_add_f32_e32 v192, -1.0, v188
	v_fma_f32 v192, v12, v192, 1.0
	v_mul_f32_e32 v180, v212, v192
	v_add_f32_e32 v192, -1.0, v189
	v_fma_f32 v192, v13, v192, 1.0
	v_mul_f32_e32 v181, v213, v192
	v_add_f32_e32 v192, -1.0, v190
	v_fma_f32 v192, v14, v192, 1.0
	v_mul_f32_e32 v182, v214, v192
	v_add_f32_e32 v192, -1.0, v191
	v_fma_f32 v192, v15, v192, 1.0
	v_mul_f32_e32 v183, v215, v192
	v_max_f32_e32 v200, 0x179abe15, v200
	v_rsq_f32_e32 v201, v200
	v_mul_f32_e32 v192, v136, v176
	v_mul_f32_e32 v202, v16, v192
	v_mul_f32_e32 v160, v160, v201
	v_mul_f32_e32 v161, v161, v201
	v_mul_f32_e32 v162, v162, v201
	v_mul_f32_e32 v163, v163, v201
	v_mul_f32_e32 v164, v164, v201
	v_mul_f32_e32 v165, v165, v201
	v_mul_f32_e32 v166, v166, v201
	v_mul_f32_e32 v167, v167, v201
	v_mul_f32_e32 v168, v184, v160
	v_mul_f32_e32 v169, v185, v161
	v_mul_f32_e32 v170, v186, v162
	v_mul_f32_e32 v171, v187, v163
	v_mul_f32_e32 v172, v188, v164
	v_mul_f32_e32 v173, v189, v165
	v_mul_f32_e32 v174, v190, v166
	v_mul_f32_e32 v175, v191, v167
	ds_write_b128 v54, v[160:163] offset:0
	ds_write_b128 v54, v[164:167] offset:16
	ds_write_b128 v54, v[168:171] offset:256
	ds_write_b128 v54, v[172:175] offset:272
	v_mul_f32_e32 v192, v137, v177
	v_fmac_f32_e32 v202, v17, v192
	v_mul_f32_e32 v192, v138, v178
	v_fmac_f32_e32 v202, v18, v192
	v_mul_f32_e32 v192, v139, v179
	v_fmac_f32_e32 v202, v19, v192
	v_mul_f32_e32 v192, v140, v180
	v_fmac_f32_e32 v202, v20, v192
	v_mul_f32_e32 v192, v141, v181
	v_fmac_f32_e32 v202, v21, v192
	v_mul_f32_e32 v192, v142, v182
	v_fmac_f32_e32 v202, v22, v192
	v_mul_f32_e32 v192, v143, v183
	v_fmac_f32_e32 v202, v23, v192
	ds_write_b128 v54, v[176:179] offset:512
	ds_write_b128 v54, v[180:183] offset:528
	v_add_f32_dpp v202, v202, v202 quad_perm:[1,0,3,2] row_mask:0xf bank_mask:0xf bound_ctrl:1
	ds_write_b128 v54, v[136:139] offset:768
	ds_write_b128 v54, v[140:143] offset:784
	v_add_f32_dpp v202, v202, v202 quad_perm:[2,3,0,1] row_mask:0xf bank_mask:0xf bound_ctrl:1
	ds_write_b128 v54, v[152:155] offset:1024
	ds_write_b128 v54, v[156:159] offset:1040
	v_add_f32_dpp v202, v202, v202 row_half_mirror row_mask:0xf bank_mask:0xf bound_ctrl:1
	v_add_u32_e32 v205, s90, v56
	v_lshl_add_u32 v205, v205, 7, s64
	s_and_saveexec_b64 s[56:57], s[8:9]
	global_store_dword v205, v202, s[24:25]
	s_or_b64 exec, exec, s[56:57]
	v_add_u32_e32 v56, v59, v56
	s_waitcnt lgkmcnt(0)
	s_barrier
	ds_read_b128 v[184:187], v55 offset:4096
	ds_read_b128 v[188:191], v55 offset:4112
	s_waitcnt vmcnt(9)
	v_lshlrev_b32_e32 v136, 16, v100
	v_lshlrev_b32_e32 v192, 16, v112
	v_lshlrev_b32_e32 v193, 16, v124
	v_add_f32_e32 v193, v193, v192
	v_fma_f32 v192, v193, 0.5, -v136
	v_fmac_f32_e32 v136, v24, v192
	v_and_b32_e32 v137, 0xffff0000, v100
	v_and_b32_e32 v192, 0xffff0000, v112
	v_and_b32_e32 v193, 0xffff0000, v124
	v_add_f32_e32 v193, v193, v192
	v_fma_f32 v192, v193, 0.5, -v137
	v_fmac_f32_e32 v137, v25, v192
	v_lshlrev_b32_e32 v138, 16, v101
	v_lshlrev_b32_e32 v192, 16, v113
	v_lshlrev_b32_e32 v193, 16, v125
	v_add_f32_e32 v193, v193, v192
	v_fma_f32 v192, v193, 0.5, -v138
	v_fmac_f32_e32 v138, v26, v192
	v_and_b32_e32 v139, 0xffff0000, v101
	v_and_b32_e32 v192, 0xffff0000, v113
	v_and_b32_e32 v193, 0xffff0000, v125
	v_add_f32_e32 v193, v193, v192
	v_fma_f32 v192, v193, 0.5, -v139
	v_fmac_f32_e32 v139, v27, v192
	v_lshlrev_b32_e32 v140, 16, v102
	v_lshlrev_b32_e32 v192, 16, v114
	v_lshlrev_b32_e32 v193, 16, v126
	v_add_f32_e32 v193, v193, v192
	v_fma_f32 v192, v193, 0.5, -v140
	v_fmac_f32_e32 v140, v28, v192
	v_and_b32_e32 v141, 0xffff0000, v102
	v_and_b32_e32 v192, 0xffff0000, v114
	v_and_b32_e32 v193, 0xffff0000, v126
	v_add_f32_e32 v193, v193, v192
	v_fma_f32 v192, v193, 0.5, -v141
	v_fmac_f32_e32 v141, v29, v192
	v_lshlrev_b32_e32 v142, 16, v103
	v_lshlrev_b32_e32 v192, 16, v115
	v_lshlrev_b32_e32 v193, 16, v127
	v_add_f32_e32 v193, v193, v192
	v_fma_f32 v192, v193, 0.5, -v142
	v_fmac_f32_e32 v142, v30, v192
	v_and_b32_e32 v143, 0xffff0000, v103
	v_and_b32_e32 v192, 0xffff0000, v115
	v_and_b32_e32 v193, 0xffff0000, v127
	v_add_f32_e32 v193, v193, v192
	v_fma_f32 v192, v193, 0.5, -v143
	v_fmac_f32_e32 v143, v31, v192
	v_lshlrev_b32_e32 v208, 16, v104
	v_lshlrev_b32_e32 v192, 16, v116
	v_lshlrev_b32_e32 v193, 16, v128
	v_add_f32_e32 v193, v193, v192
	v_fma_f32 v192, v193, 0.5, -v208
	v_fmac_f32_e32 v208, v32, v192
	v_and_b32_e32 v209, 0xffff0000, v104
	v_and_b32_e32 v192, 0xffff0000, v116
	v_and_b32_e32 v193, 0xffff0000, v128
	v_add_f32_e32 v193, v193, v192
	v_fma_f32 v192, v193, 0.5, -v209
	v_fmac_f32_e32 v209, v33, v192
	v_lshlrev_b32_e32 v210, 16, v105
	v_lshlrev_b32_e32 v192, 16, v117
	v_lshlrev_b32_e32 v193, 16, v129
	v_add_f32_e32 v193, v193, v192
	v_fma_f32 v192, v193, 0.5, -v210
	v_fmac_f32_e32 v210, v34, v192
	v_and_b32_e32 v211, 0xffff0000, v105
	v_and_b32_e32 v192, 0xffff0000, v117
	v_and_b32_e32 v193, 0xffff0000, v129
	v_add_f32_e32 v193, v193, v192
	v_fma_f32 v192, v193, 0.5, -v211
	v_fmac_f32_e32 v211, v35, v192
	v_lshlrev_b32_e32 v212, 16, v106
	v_lshlrev_b32_e32 v192, 16, v118
	v_lshlrev_b32_e32 v193, 16, v130
	v_add_f32_e32 v193, v193, v192
	v_fma_f32 v192, v193, 0.5, -v212
	v_fmac_f32_e32 v212, v36, v192
	v_and_b32_e32 v213, 0xffff0000, v106
	v_and_b32_e32 v192, 0xffff0000, v118
	v_and_b32_e32 v193, 0xffff0000, v130
	v_add_f32_e32 v193, v193, v192
	v_fma_f32 v192, v193, 0.5, -v213
	v_fmac_f32_e32 v213, v37, v192
	v_lshlrev_b32_e32 v214, 16, v107
	v_lshlrev_b32_e32 v192, 16, v119
	v_lshlrev_b32_e32 v193, 16, v131
	v_add_f32_e32 v193, v193, v192
	v_fma_f32 v192, v193, 0.5, -v214
	v_fmac_f32_e32 v214, v38, v192
	v_and_b32_e32 v215, 0xffff0000, v107
	v_and_b32_e32 v192, 0xffff0000, v119
	v_and_b32_e32 v193, 0xffff0000, v131
	v_add_f32_e32 v193, v193, v192
	v_fma_f32 v192, v193, 0.5, -v215
	v_fmac_f32_e32 v215, v39, v192
	v_lshlrev_b32_e32 v152, 16, v108
	v_lshlrev_b32_e32 v192, 16, v120
	v_lshlrev_b32_e32 v193, 16, v132
	v_add_f32_e32 v193, v193, v192
	v_fma_f32 v192, v193, 0.5, -v152
	v_fmac_f32_e32 v152, v40, v192
	v_and_b32_e32 v153, 0xffff0000, v108
	v_and_b32_e32 v192, 0xffff0000, v120
	v_and_b32_e32 v193, 0xffff0000, v132
	v_add_f32_e32 v193, v193, v192
	v_fma_f32 v192, v193, 0.5, -v153
	v_fmac_f32_e32 v153, v41, v192
	v_lshlrev_b32_e32 v154, 16, v109
	v_lshlrev_b32_e32 v192, 16, v121
	v_lshlrev_b32_e32 v193, 16, v133
	v_add_f32_e32 v193, v193, v192
	v_fma_f32 v192, v193, 0.5, -v154
	v_fmac_f32_e32 v154, v42, v192
	v_and_b32_e32 v155, 0xffff0000, v109
	v_and_b32_e32 v192, 0xffff0000, v121
	v_and_b32_e32 v193, 0xffff0000, v133
	v_add_f32_e32 v193, v193, v192
	v_fma_f32 v192, v193, 0.5, -v155
	v_fmac_f32_e32 v155, v43, v192
	v_lshlrev_b32_e32 v156, 16, v110
	v_lshlrev_b32_e32 v192, 16, v122
	v_lshlrev_b32_e32 v193, 16, v134
	v_add_f32_e32 v193, v193, v192
	v_fma_f32 v192, v193, 0.5, -v156
	v_fmac_f32_e32 v156, v44, v192
	v_and_b32_e32 v157, 0xffff0000, v110
	v_and_b32_e32 v192, 0xffff0000, v122
	v_and_b32_e32 v193, 0xffff0000, v134
	v_add_f32_e32 v193, v193, v192
	v_fma_f32 v192, v193, 0.5, -v157
	v_fmac_f32_e32 v157, v45, v192
	v_lshlrev_b32_e32 v158, 16, v111
	v_lshlrev_b32_e32 v192, 16, v123
	v_lshlrev_b32_e32 v193, 16, v135
	v_add_f32_e32 v193, v193, v192
	v_fma_f32 v192, v193, 0.5, -v158
	v_fmac_f32_e32 v158, v46, v192
	v_and_b32_e32 v159, 0xffff0000, v111
	v_and_b32_e32 v192, 0xffff0000, v123
	v_and_b32_e32 v193, 0xffff0000, v135
	v_add_f32_e32 v193, v193, v192
	v_fma_f32 v192, v193, 0.5, -v159
	v_fmac_f32_e32 v159, v47, v192
	v_add_u32_e32 v57, v59, v56
	v_add_u32_e32 v57, v59, v57
	v_cmp_lt_i32_e64 s[4:5], 0, v57
	v_cmp_gt_i32_e64 s[58:59], v58, v57
	v_mad_u32_u24 v205, v57, v53, v52
	s_nop 0
	v_cndmask_b32_e64 v206, 0, v53, s[4:5]
	v_cndmask_b32_e64 v207, 0, v53, s[58:59]
	v_cndmask_b32_e64 v62, 0, 1.0, s[4:5]
	v_cndmask_b32_e64 v63, 0, 1.0, s[58:59]
	v_sub_u32_e32 v206, v205, v206
	v_add_u32_e32 v207, v205, v207
	global_load_dwordx4 v[100:103], v205, s[72:73] offset:-2048
	global_load_dwordx4 v[104:107], v205, s[72:73]
	global_load_dwordx4 v[108:111], v205, s[72:73] offset:2048
	global_load_dwordx4 v[112:115], v206, s[72:73] offset:-2048
	global_load_dwordx4 v[116:119], v206, s[72:73]
	global_load_dwordx4 v[120:123], v206, s[72:73] offset:2048
	global_load_dwordx4 v[124:127], v207, s[72:73] offset:-2048
	global_load_dwordx4 v[128:131], v207, s[72:73]
	global_load_dwordx4 v[132:135], v207, s[72:73] offset:2048
	v_mul_f32_e32 v160, v0, v208
	v_mul_f32_e32 v161, v1, v209
	v_mul_f32_e32 v162, v2, v210
	v_mul_f32_e32 v163, v3, v211
	v_mul_f32_e32 v164, v4, v212
	v_mul_f32_e32 v165, v5, v213
	v_mul_f32_e32 v166, v6, v214
	v_mul_f32_e32 v167, v7, v215
	v_mul_f32_e32 v200, v160, v160
	v_fmac_f32_e32 v200, v161, v161
	v_fmac_f32_e32 v200, v162, v162
	v_fmac_f32_e32 v200, v163, v163
	v_fmac_f32_e32 v200, v164, v164
	v_fmac_f32_e32 v200, v165, v165
	v_fmac_f32_e32 v200, v166, v166
	v_fmac_f32_e32 v200, v167, v167
	s_waitcnt lgkmcnt(0)
	v_add_f32_e32 v192, -1.0, v184
	v_fma_f32 v192, v8, v192, 1.0
	v_mul_f32_e32 v176, v208, v192
	v_add_f32_dpp v200, v200, v200 quad_perm:[1,0,3,2] row_mask:0xf bank_mask:0xf bound_ctrl:1
	v_add_f32_e32 v192, -1.0, v185
	v_fma_f32 v192, v9, v192, 1.0
	v_mul_f32_e32 v177, v209, v192
	v_add_f32_dpp v200, v200, v200 quad_perm:[2,3,0,1] row_mask:0xf bank_mask:0xf bound_ctrl:1
	v_add_f32_e32 v192, -1.0, v186
	v_fma_f32 v192, v10, v192, 1.0
	v_mul_f32_e32 v178, v210, v192
	v_add_f32_dpp v200, v200, v200 row_half_mirror row_mask:0xf bank_mask:0xf bound_ctrl:1
	v_add_f32_e32 v192, -1.0, v187
	v_fma_f32 v192, v11, v192, 1.0
	v_mul_f32_e32 v179, v211, v192
	v_add_f32_e32 v192, -1.0, v188
	v_fma_f32 v192, v12, v192, 1.0
	v_mul_f32_e32 v180, v212, v192
	v_add_f32_e32 v192, -1.0, v189
	v_fma_f32 v192, v13, v192, 1.0
	v_mul_f32_e32 v181, v213, v192
	v_add_f32_e32 v192, -1.0, v190
	v_fma_f32 v192, v14, v192, 1.0
	v_mul_f32_e32 v182, v214, v192
	v_add_f32_e32 v192, -1.0, v191
	v_fma_f32 v192, v15, v192, 1.0
	v_mul_f32_e32 v183, v215, v192
	v_max_f32_e32 v200, 0x179abe15, v200
	v_rsq_f32_e32 v201, v200
	v_mul_f32_e32 v192, v136, v176
	v_mul_f32_e32 v202, v16, v192
	v_mul_f32_e32 v160, v160, v201
	v_mul_f32_e32 v161, v161, v201
	v_mul_f32_e32 v162, v162, v201
	v_mul_f32_e32 v163, v163, v201
	v_mul_f32_e32 v164, v164, v201
	v_mul_f32_e32 v165, v165, v201
	v_mul_f32_e32 v166, v166, v201
	v_mul_f32_e32 v167, v167, v201
	v_mul_f32_e32 v168, v184, v160
	v_mul_f32_e32 v169, v185, v161
	v_mul_f32_e32 v170, v186, v162
	v_mul_f32_e32 v171, v187, v163
	v_mul_f32_e32 v172, v188, v164
	v_mul_f32_e32 v173, v189, v165
	v_mul_f32_e32 v174, v190, v166
	v_mul_f32_e32 v175, v191, v167
	ds_write_b128 v54, v[160:163] offset:20480
	ds_write_b128 v54, v[164:167] offset:20496
	ds_write_b128 v54, v[168:171] offset:20736
	ds_write_b128 v54, v[172:175] offset:20752
	v_mul_f32_e32 v192, v137, v177
	v_fmac_f32_e32 v202, v17, v192
	v_mul_f32_e32 v192, v138, v178
	v_fmac_f32_e32 v202, v18, v192
	v_mul_f32_e32 v192, v139, v179
	v_fmac_f32_e32 v202, v19, v192
	v_mul_f32_e32 v192, v140, v180
	v_fmac_f32_e32 v202, v20, v192
	v_mul_f32_e32 v192, v141, v181
	v_fmac_f32_e32 v202, v21, v192
	v_mul_f32_e32 v192, v142, v182
	v_fmac_f32_e32 v202, v22, v192
	v_mul_f32_e32 v192, v143, v183
	v_fmac_f32_e32 v202, v23, v192
	ds_write_b128 v54, v[176:179] offset:20992
	ds_write_b128 v54, v[180:183] offset:21008
	v_add_f32_dpp v202, v202, v202 quad_perm:[1,0,3,2] row_mask:0xf bank_mask:0xf bound_ctrl:1
	ds_write_b128 v54, v[136:139] offset:21248
	ds_write_b128 v54, v[140:143] offset:21264
	v_add_f32_dpp v202, v202, v202 quad_perm:[2,3,0,1] row_mask:0xf bank_mask:0xf bound_ctrl:1
	ds_write_b128 v54, v[152:155] offset:21504
	ds_write_b128 v54, v[156:159] offset:21520
	v_add_f32_dpp v202, v202, v202 row_half_mirror row_mask:0xf bank_mask:0xf bound_ctrl:1
	v_add_u32_e32 v205, s90, v56
	v_lshl_add_u32 v205, v205, 7, s64
	s_and_saveexec_b64 s[56:57], s[8:9]
	global_store_dword v205, v202, s[24:25]
	s_or_b64 exec, exec, s[56:57]
	v_add_u32_e32 v56, v59, v56
	s_waitcnt lgkmcnt(0)
	s_barrier
	s_add_i32 s10, s10, 2
	s_cmp_lt_u32 s10, 127
	s_cbranch_scc1 .Lmy_ks_loop
	ds_read_b128 v[184:187], v55 offset:0
	ds_read_b128 v[188:191], v55 offset:16
	s_waitcnt vmcnt(9)
	v_lshlrev_b32_e32 v136, 16, v64
	v_lshlrev_b32_e32 v192, 16, v76
	v_lshlrev_b32_e32 v193, 16, v88
	v_mul_f32_e32 v193, v61, v193
	v_fmac_f32_e32 v193, v60, v192
	v_fma_f32 v192, v193, 0.5, -v136
	v_fmac_f32_e32 v136, v24, v192
	v_and_b32_e32 v137, 0xffff0000, v64
	v_and_b32_e32 v192, 0xffff0000, v76
	v_and_b32_e32 v193, 0xffff0000, v88
	v_mul_f32_e32 v193, v61, v193
	v_fmac_f32_e32 v193, v60, v192
	v_fma_f32 v192, v193, 0.5, -v137
	v_fmac_f32_e32 v137, v25, v192
	v_lshlrev_b32_e32 v138, 16, v65
	v_lshlrev_b32_e32 v192, 16, v77
	v_lshlrev_b32_e32 v193, 16, v89
	v_mul_f32_e32 v193, v61, v193
	v_fmac_f32_e32 v193, v60, v192
	v_fma_f32 v192, v193, 0.5, -v138
	v_fmac_f32_e32 v138, v26, v192
	v_and_b32_e32 v139, 0xffff0000, v65
	v_and_b32_e32 v192, 0xffff0000, v77
	v_and_b32_e32 v193, 0xffff0000, v89
	v_mul_f32_e32 v193, v61, v193
	v_fmac_f32_e32 v193, v60, v192
	v_fma_f32 v192, v193, 0.5, -v139
	v_fmac_f32_e32 v139, v27, v192
	v_lshlrev_b32_e32 v140, 16, v66
	v_lshlrev_b32_e32 v192, 16, v78
	v_lshlrev_b32_e32 v193, 16, v90
	v_mul_f32_e32 v193, v61, v193
	v_fmac_f32_e32 v193, v60, v192
	v_fma_f32 v192, v193, 0.5, -v140
	v_fmac_f32_e32 v140, v28, v192
	v_and_b32_e32 v141, 0xffff0000, v66
	v_and_b32_e32 v192, 0xffff0000, v78
	v_and_b32_e32 v193, 0xffff0000, v90
	v_mul_f32_e32 v193, v61, v193
	v_fmac_f32_e32 v193, v60, v192
	v_fma_f32 v192, v193, 0.5, -v141
	v_fmac_f32_e32 v141, v29, v192
	v_lshlrev_b32_e32 v142, 16, v67
	v_lshlrev_b32_e32 v192, 16, v79
	v_lshlrev_b32_e32 v193, 16, v91
	v_mul_f32_e32 v193, v61, v193
	v_fmac_f32_e32 v193, v60, v192
	v_fma_f32 v192, v193, 0.5, -v142
	v_fmac_f32_e32 v142, v30, v192
	v_and_b32_e32 v143, 0xffff0000, v67
	v_and_b32_e32 v192, 0xffff0000, v79
	v_and_b32_e32 v193, 0xffff0000, v91
	v_mul_f32_e32 v193, v61, v193
	v_fmac_f32_e32 v193, v60, v192
	v_fma_f32 v192, v193, 0.5, -v143
	v_fmac_f32_e32 v143, v31, v192
	v_lshlrev_b32_e32 v208, 16, v68
	v_lshlrev_b32_e32 v192, 16, v80
	v_lshlrev_b32_e32 v193, 16, v92
	v_mul_f32_e32 v193, v61, v193
	v_fmac_f32_e32 v193, v60, v192
	v_fma_f32 v192, v193, 0.5, -v208
	v_fmac_f32_e32 v208, v32, v192
	v_and_b32_e32 v209, 0xffff0000, v68
	v_and_b32_e32 v192, 0xffff0000, v80
	v_and_b32_e32 v193, 0xffff0000, v92
	v_mul_f32_e32 v193, v61, v193
	v_fmac_f32_e32 v193, v60, v192
	v_fma_f32 v192, v193, 0.5, -v209
	v_fmac_f32_e32 v209, v33, v192
	v_lshlrev_b32_e32 v210, 16, v69
	v_lshlrev_b32_e32 v192, 16, v81
	v_lshlrev_b32_e32 v193, 16, v93
	v_mul_f32_e32 v193, v61, v193
	v_fmac_f32_e32 v193, v60, v192
	v_fma_f32 v192, v193, 0.5, -v210
	v_fmac_f32_e32 v210, v34, v192
	v_and_b32_e32 v211, 0xffff0000, v69
	v_and_b32_e32 v192, 0xffff0000, v81
	v_and_b32_e32 v193, 0xffff0000, v93
	v_mul_f32_e32 v193, v61, v193
	v_fmac_f32_e32 v193, v60, v192
	v_fma_f32 v192, v193, 0.5, -v211
	v_fmac_f32_e32 v211, v35, v192
	v_lshlrev_b32_e32 v212, 16, v70
	v_lshlrev_b32_e32 v192, 16, v82
	v_lshlrev_b32_e32 v193, 16, v94
	v_mul_f32_e32 v193, v61, v193
	v_fmac_f32_e32 v193, v60, v192
	v_fma_f32 v192, v193, 0.5, -v212
	v_fmac_f32_e32 v212, v36, v192
	v_and_b32_e32 v213, 0xffff0000, v70
	v_and_b32_e32 v192, 0xffff0000, v82
	v_and_b32_e32 v193, 0xffff0000, v94
	v_mul_f32_e32 v193, v61, v193
	v_fmac_f32_e32 v193, v60, v192
	v_fma_f32 v192, v193, 0.5, -v213
	v_fmac_f32_e32 v213, v37, v192
	v_lshlrev_b32_e32 v214, 16, v71
	v_lshlrev_b32_e32 v192, 16, v83
	v_lshlrev_b32_e32 v193, 16, v95
	v_mul_f32_e32 v193, v61, v193
	v_fmac_f32_e32 v193, v60, v192
	v_fma_f32 v192, v193, 0.5, -v214
	v_fmac_f32_e32 v214, v38, v192
	v_and_b32_e32 v215, 0xffff0000, v71
	v_and_b32_e32 v192, 0xffff0000, v83
	v_and_b32_e32 v193, 0xffff0000, v95
	v_mul_f32_e32 v193, v61, v193
	v_fmac_f32_e32 v193, v60, v192
	v_fma_f32 v192, v193, 0.5, -v215
	v_fmac_f32_e32 v215, v39, v192
	v_lshlrev_b32_e32 v152, 16, v72
	v_lshlrev_b32_e32 v192, 16, v84
	v_lshlrev_b32_e32 v193, 16, v96
	v_mul_f32_e32 v193, v61, v193
	v_fmac_f32_e32 v193, v60, v192
	v_fma_f32 v192, v193, 0.5, -v152
	v_fmac_f32_e32 v152, v40, v192
	v_and_b32_e32 v153, 0xffff0000, v72
	v_and_b32_e32 v192, 0xffff0000, v84
	v_and_b32_e32 v193, 0xffff0000, v96
	v_mul_f32_e32 v193, v61, v193
	v_fmac_f32_e32 v193, v60, v192
	v_fma_f32 v192, v193, 0.5, -v153
	v_fmac_f32_e32 v153, v41, v192
	v_lshlrev_b32_e32 v154, 16, v73
	v_lshlrev_b32_e32 v192, 16, v85
	v_lshlrev_b32_e32 v193, 16, v97
	v_mul_f32_e32 v193, v61, v193
	v_fmac_f32_e32 v193, v60, v192
	v_fma_f32 v192, v193, 0.5, -v154
	v_fmac_f32_e32 v154, v42, v192
	v_and_b32_e32 v155, 0xffff0000, v73
	v_and_b32_e32 v192, 0xffff0000, v85
	v_and_b32_e32 v193, 0xffff0000, v97
	v_mul_f32_e32 v193, v61, v193
	v_fmac_f32_e32 v193, v60, v192
	v_fma_f32 v192, v193, 0.5, -v155
	v_fmac_f32_e32 v155, v43, v192
	v_lshlrev_b32_e32 v156, 16, v74
	v_lshlrev_b32_e32 v192, 16, v86
	v_lshlrev_b32_e32 v193, 16, v98
	v_mul_f32_e32 v193, v61, v193
	v_fmac_f32_e32 v193, v60, v192
	v_fma_f32 v192, v193, 0.5, -v156
	v_fmac_f32_e32 v156, v44, v192
	v_and_b32_e32 v157, 0xffff0000, v74
	v_and_b32_e32 v192, 0xffff0000, v86
	v_and_b32_e32 v193, 0xffff0000, v98
	v_mul_f32_e32 v193, v61, v193
	v_fmac_f32_e32 v193, v60, v192
	v_fma_f32 v192, v193, 0.5, -v157
	v_fmac_f32_e32 v157, v45, v192
	v_lshlrev_b32_e32 v158, 16, v75
	v_lshlrev_b32_e32 v192, 16, v87
	v_lshlrev_b32_e32 v193, 16, v99
	v_mul_f32_e32 v193, v61, v193
	v_fmac_f32_e32 v193, v60, v192
	v_fma_f32 v192, v193, 0.5, -v158
	v_fmac_f32_e32 v158, v46, v192
	v_and_b32_e32 v159, 0xffff0000, v75
	v_and_b32_e32 v192, 0xffff0000, v87
	v_and_b32_e32 v193, 0xffff0000, v99
	v_mul_f32_e32 v193, v61, v193
	v_fmac_f32_e32 v193, v60, v192
	v_fma_f32 v192, v193, 0.5, -v159
	v_fmac_f32_e32 v159, v47, v192
	v_mul_f32_e32 v160, v0, v208
	v_mul_f32_e32 v161, v1, v209
	v_mul_f32_e32 v162, v2, v210
	v_mul_f32_e32 v163, v3, v211
	v_mul_f32_e32 v164, v4, v212
	v_mul_f32_e32 v165, v5, v213
	v_mul_f32_e32 v166, v6, v214
	v_mul_f32_e32 v167, v7, v215
	v_mul_f32_e32 v200, v160, v160
	v_fmac_f32_e32 v200, v161, v161
	v_fmac_f32_e32 v200, v162, v162
	v_fmac_f32_e32 v200, v163, v163
	v_fmac_f32_e32 v200, v164, v164
	v_fmac_f32_e32 v200, v165, v165
	v_fmac_f32_e32 v200, v166, v166
	v_fmac_f32_e32 v200, v167, v167
	s_waitcnt lgkmcnt(0)
	v_add_f32_e32 v192, -1.0, v184
	v_fma_f32 v192, v8, v192, 1.0
	v_mul_f32_e32 v176, v208, v192
	v_add_f32_dpp v200, v200, v200 quad_perm:[1,0,3,2] row_mask:0xf bank_mask:0xf bound_ctrl:1
	v_add_f32_e32 v192, -1.0, v185
	v_fma_f32 v192, v9, v192, 1.0
	v_mul_f32_e32 v177, v209, v192
	v_add_f32_dpp v200, v200, v200 quad_perm:[2,3,0,1] row_mask:0xf bank_mask:0xf bound_ctrl:1
	v_add_f32_e32 v192, -1.0, v186
	v_fma_f32 v192, v10, v192, 1.0
	v_mul_f32_e32 v178, v210, v192
	v_add_f32_dpp v200, v200, v200 row_half_mirror row_mask:0xf bank_mask:0xf bound_ctrl:1
	v_add_f32_e32 v192, -1.0, v187
	v_fma_f32 v192, v11, v192, 1.0
	v_mul_f32_e32 v179, v211, v192
	v_add_f32_e32 v192, -1.0, v188
	v_fma_f32 v192, v12, v192, 1.0
	v_mul_f32_e32 v180, v212, v192
	v_add_f32_e32 v192, -1.0, v189
	v_fma_f32 v192, v13, v192, 1.0
	v_mul_f32_e32 v181, v213, v192
	v_add_f32_e32 v192, -1.0, v190
	v_fma_f32 v192, v14, v192, 1.0
	v_mul_f32_e32 v182, v214, v192
	v_add_f32_e32 v192, -1.0, v191
	v_fma_f32 v192, v15, v192, 1.0
	v_mul_f32_e32 v183, v215, v192
	v_max_f32_e32 v200, 0x179abe15, v200
	v_rsq_f32_e32 v201, v200
	v_mul_f32_e32 v192, v136, v176
	v_mul_f32_e32 v202, v16, v192
	v_mul_f32_e32 v160, v160, v201
	v_mul_f32_e32 v161, v161, v201
	v_mul_f32_e32 v162, v162, v201
	v_mul_f32_e32 v163, v163, v201
	v_mul_f32_e32 v164, v164, v201
	v_mul_f32_e32 v165, v165, v201
	v_mul_f32_e32 v166, v166, v201
	v_mul_f32_e32 v167, v167, v201
	v_mul_f32_e32 v168, v184, v160
	v_mul_f32_e32 v169, v185, v161
	v_mul_f32_e32 v170, v186, v162
	v_mul_f32_e32 v171, v187, v163
	v_mul_f32_e32 v172, v188, v164
	v_mul_f32_e32 v173, v189, v165
	v_mul_f32_e32 v174, v190, v166
	v_mul_f32_e32 v175, v191, v167
	ds_write_b128 v54, v[160:163] offset:0
	ds_write_b128 v54, v[164:167] offset:16
	ds_write_b128 v54, v[168:171] offset:256
	ds_write_b128 v54, v[172:175] offset:272
	v_mul_f32_e32 v192, v137, v177
	v_fmac_f32_e32 v202, v17, v192
	v_mul_f32_e32 v192, v138, v178
	v_fmac_f32_e32 v202, v18, v192
	v_mul_f32_e32 v192, v139, v179
	v_fmac_f32_e32 v202, v19, v192
	v_mul_f32_e32 v192, v140, v180
	v_fmac_f32_e32 v202, v20, v192
	v_mul_f32_e32 v192, v141, v181
	v_fmac_f32_e32 v202, v21, v192
	v_mul_f32_e32 v192, v142, v182
	v_fmac_f32_e32 v202, v22, v192
	v_mul_f32_e32 v192, v143, v183
	v_fmac_f32_e32 v202, v23, v192
	ds_write_b128 v54, v[176:179] offset:512
	ds_write_b128 v54, v[180:183] offset:528
	v_add_f32_dpp v202, v202, v202 quad_perm:[1,0,3,2] row_mask:0xf bank_mask:0xf bound_ctrl:1
	ds_write_b128 v54, v[136:139] offset:768
	ds_write_b128 v54, v[140:143] offset:784
	v_add_f32_dpp v202, v202, v202 quad_perm:[2,3,0,1] row_mask:0xf bank_mask:0xf bound_ctrl:1
	ds_write_b128 v54, v[152:155] offset:1024
	ds_write_b128 v54, v[156:159] offset:1040
	v_add_f32_dpp v202, v202, v202 row_half_mirror row_mask:0xf bank_mask:0xf bound_ctrl:1
	v_add_u32_e32 v205, s90, v56
	v_lshl_add_u32 v205, v205, 7, s64
	s_and_saveexec_b64 s[56:57], s[8:9]
	global_store_dword v205, v202, s[24:25]
	s_or_b64 exec, exec, s[56:57]
	v_add_u32_e32 v56, v59, v56
	s_waitcnt lgkmcnt(0)
	s_barrier
	ds_read_b128 v[184:187], v55 offset:4096
	ds_read_b128 v[188:191], v55 offset:4112
	s_waitcnt vmcnt(0)
	v_lshlrev_b32_e32 v136, 16, v100
	v_lshlrev_b32_e32 v192, 16, v112
	v_lshlrev_b32_e32 v193, 16, v124
	v_mul_f32_e32 v193, v63, v193
	v_fmac_f32_e32 v193, v62, v192
	v_fma_f32 v192, v193, 0.5, -v136
	v_fmac_f32_e32 v136, v24, v192
	v_and_b32_e32 v137, 0xffff0000, v100
	v_and_b32_e32 v192, 0xffff0000, v112
	v_and_b32_e32 v193, 0xffff0000, v124
	v_mul_f32_e32 v193, v63, v193
	v_fmac_f32_e32 v193, v62, v192
	v_fma_f32 v192, v193, 0.5, -v137
	v_fmac_f32_e32 v137, v25, v192
	v_lshlrev_b32_e32 v138, 16, v101
	v_lshlrev_b32_e32 v192, 16, v113
	v_lshlrev_b32_e32 v193, 16, v125
	v_mul_f32_e32 v193, v63, v193
	v_fmac_f32_e32 v193, v62, v192
	v_fma_f32 v192, v193, 0.5, -v138
	v_fmac_f32_e32 v138, v26, v192
	v_and_b32_e32 v139, 0xffff0000, v101
	v_and_b32_e32 v192, 0xffff0000, v113
	v_and_b32_e32 v193, 0xffff0000, v125
	v_mul_f32_e32 v193, v63, v193
	v_fmac_f32_e32 v193, v62, v192
	v_fma_f32 v192, v193, 0.5, -v139
	v_fmac_f32_e32 v139, v27, v192
	v_lshlrev_b32_e32 v140, 16, v102
	v_lshlrev_b32_e32 v192, 16, v114
	v_lshlrev_b32_e32 v193, 16, v126
	v_mul_f32_e32 v193, v63, v193
	v_fmac_f32_e32 v193, v62, v192
	v_fma_f32 v192, v193, 0.5, -v140
	v_fmac_f32_e32 v140, v28, v192
	v_and_b32_e32 v141, 0xffff0000, v102
	v_and_b32_e32 v192, 0xffff0000, v114
	v_and_b32_e32 v193, 0xffff0000, v126
	v_mul_f32_e32 v193, v63, v193
	v_fmac_f32_e32 v193, v62, v192
	v_fma_f32 v192, v193, 0.5, -v141
	v_fmac_f32_e32 v141, v29, v192
	v_lshlrev_b32_e32 v142, 16, v103
	v_lshlrev_b32_e32 v192, 16, v115
	v_lshlrev_b32_e32 v193, 16, v127
	v_mul_f32_e32 v193, v63, v193
	v_fmac_f32_e32 v193, v62, v192
	v_fma_f32 v192, v193, 0.5, -v142
	v_fmac_f32_e32 v142, v30, v192
	v_and_b32_e32 v143, 0xffff0000, v103
	v_and_b32_e32 v192, 0xffff0000, v115
	v_and_b32_e32 v193, 0xffff0000, v127
	v_mul_f32_e32 v193, v63, v193
	v_fmac_f32_e32 v193, v62, v192
	v_fma_f32 v192, v193, 0.5, -v143
	v_fmac_f32_e32 v143, v31, v192
	v_lshlrev_b32_e32 v208, 16, v104
	v_lshlrev_b32_e32 v192, 16, v116
	v_lshlrev_b32_e32 v193, 16, v128
	v_mul_f32_e32 v193, v63, v193
	v_fmac_f32_e32 v193, v62, v192
	v_fma_f32 v192, v193, 0.5, -v208
	v_fmac_f32_e32 v208, v32, v192
	v_and_b32_e32 v209, 0xffff0000, v104
	v_and_b32_e32 v192, 0xffff0000, v116
	v_and_b32_e32 v193, 0xffff0000, v128
	v_mul_f32_e32 v193, v63, v193
	v_fmac_f32_e32 v193, v62, v192
	v_fma_f32 v192, v193, 0.5, -v209
	v_fmac_f32_e32 v209, v33, v192
	v_lshlrev_b32_e32 v210, 16, v105
	v_lshlrev_b32_e32 v192, 16, v117
	v_lshlrev_b32_e32 v193, 16, v129
	v_mul_f32_e32 v193, v63, v193
	v_fmac_f32_e32 v193, v62, v192
	v_fma_f32 v192, v193, 0.5, -v210
	v_fmac_f32_e32 v210, v34, v192
	v_and_b32_e32 v211, 0xffff0000, v105
	v_and_b32_e32 v192, 0xffff0000, v117
	v_and_b32_e32 v193, 0xffff0000, v129
	v_mul_f32_e32 v193, v63, v193
	v_fmac_f32_e32 v193, v62, v192
	v_fma_f32 v192, v193, 0.5, -v211
	v_fmac_f32_e32 v211, v35, v192
	v_lshlrev_b32_e32 v212, 16, v106
	v_lshlrev_b32_e32 v192, 16, v118
	v_lshlrev_b32_e32 v193, 16, v130
	v_mul_f32_e32 v193, v63, v193
	v_fmac_f32_e32 v193, v62, v192
	v_fma_f32 v192, v193, 0.5, -v212
	v_fmac_f32_e32 v212, v36, v192
	v_and_b32_e32 v213, 0xffff0000, v106
	v_and_b32_e32 v192, 0xffff0000, v118
	v_and_b32_e32 v193, 0xffff0000, v130
	v_mul_f32_e32 v193, v63, v193
	v_fmac_f32_e32 v193, v62, v192
	v_fma_f32 v192, v193, 0.5, -v213
	v_fmac_f32_e32 v213, v37, v192
	v_lshlrev_b32_e32 v214, 16, v107
	v_lshlrev_b32_e32 v192, 16, v119
	v_lshlrev_b32_e32 v193, 16, v131
	v_mul_f32_e32 v193, v63, v193
	v_fmac_f32_e32 v193, v62, v192
	v_fma_f32 v192, v193, 0.5, -v214
	v_fmac_f32_e32 v214, v38, v192
	v_and_b32_e32 v215, 0xffff0000, v107
	v_and_b32_e32 v192, 0xffff0000, v119
	v_and_b32_e32 v193, 0xffff0000, v131
	v_mul_f32_e32 v193, v63, v193
	v_fmac_f32_e32 v193, v62, v192
	v_fma_f32 v192, v193, 0.5, -v215
	v_fmac_f32_e32 v215, v39, v192
	v_lshlrev_b32_e32 v152, 16, v108
	v_lshlrev_b32_e32 v192, 16, v120
	v_lshlrev_b32_e32 v193, 16, v132
	v_mul_f32_e32 v193, v63, v193
	v_fmac_f32_e32 v193, v62, v192
	v_fma_f32 v192, v193, 0.5, -v152
	v_fmac_f32_e32 v152, v40, v192
	v_and_b32_e32 v153, 0xffff0000, v108
	v_and_b32_e32 v192, 0xffff0000, v120
	v_and_b32_e32 v193, 0xffff0000, v132
	v_mul_f32_e32 v193, v63, v193
	v_fmac_f32_e32 v193, v62, v192
	v_fma_f32 v192, v193, 0.5, -v153
	v_fmac_f32_e32 v153, v41, v192
	v_lshlrev_b32_e32 v154, 16, v109
	v_lshlrev_b32_e32 v192, 16, v121
	v_lshlrev_b32_e32 v193, 16, v133
	v_mul_f32_e32 v193, v63, v193
	v_fmac_f32_e32 v193, v62, v192
	v_fma_f32 v192, v193, 0.5, -v154
	v_fmac_f32_e32 v154, v42, v192
	v_and_b32_e32 v155, 0xffff0000, v109
	v_and_b32_e32 v192, 0xffff0000, v121
	v_and_b32_e32 v193, 0xffff0000, v133
	v_mul_f32_e32 v193, v63, v193
	v_fmac_f32_e32 v193, v62, v192
	v_fma_f32 v192, v193, 0.5, -v155
	v_fmac_f32_e32 v155, v43, v192
	v_lshlrev_b32_e32 v156, 16, v110
	v_lshlrev_b32_e32 v192, 16, v122
	v_lshlrev_b32_e32 v193, 16, v134
	v_mul_f32_e32 v193, v63, v193
	v_fmac_f32_e32 v193, v62, v192
	v_fma_f32 v192, v193, 0.5, -v156
	v_fmac_f32_e32 v156, v44, v192
	v_and_b32_e32 v157, 0xffff0000, v110
	v_and_b32_e32 v192, 0xffff0000, v122
	v_and_b32_e32 v193, 0xffff0000, v134
	v_mul_f32_e32 v193, v63, v193
	v_fmac_f32_e32 v193, v62, v192
	v_fma_f32 v192, v193, 0.5, -v157
	v_fmac_f32_e32 v157, v45, v192
	v_lshlrev_b32_e32 v158, 16, v111
	v_lshlrev_b32_e32 v192, 16, v123
	v_lshlrev_b32_e32 v193, 16, v135
	v_mul_f32_e32 v193, v63, v193
	v_fmac_f32_e32 v193, v62, v192
	v_fma_f32 v192, v193, 0.5, -v158
	v_fmac_f32_e32 v158, v46, v192
	v_and_b32_e32 v159, 0xffff0000, v111
	v_and_b32_e32 v192, 0xffff0000, v123
	v_and_b32_e32 v193, 0xffff0000, v135
	v_mul_f32_e32 v193, v63, v193
	v_fmac_f32_e32 v193, v62, v192
	v_fma_f32 v192, v193, 0.5, -v159
	v_fmac_f32_e32 v159, v47, v192
	v_mul_f32_e32 v160, v0, v208
	v_mul_f32_e32 v161, v1, v209
	v_mul_f32_e32 v162, v2, v210
	v_mul_f32_e32 v163, v3, v211
	v_mul_f32_e32 v164, v4, v212
	v_mul_f32_e32 v165, v5, v213
	v_mul_f32_e32 v166, v6, v214
	v_mul_f32_e32 v167, v7, v215
	v_mul_f32_e32 v200, v160, v160
	v_fmac_f32_e32 v200, v161, v161
	v_fmac_f32_e32 v200, v162, v162
	v_fmac_f32_e32 v200, v163, v163
	v_fmac_f32_e32 v200, v164, v164
	v_fmac_f32_e32 v200, v165, v165
	v_fmac_f32_e32 v200, v166, v166
	v_fmac_f32_e32 v200, v167, v167
	s_waitcnt lgkmcnt(0)
	v_add_f32_e32 v192, -1.0, v184
	v_fma_f32 v192, v8, v192, 1.0
	v_mul_f32_e32 v176, v208, v192
	v_add_f32_dpp v200, v200, v200 quad_perm:[1,0,3,2] row_mask:0xf bank_mask:0xf bound_ctrl:1
	v_add_f32_e32 v192, -1.0, v185
	v_fma_f32 v192, v9, v192, 1.0
	v_mul_f32_e32 v177, v209, v192
	v_add_f32_dpp v200, v200, v200 quad_perm:[2,3,0,1] row_mask:0xf bank_mask:0xf bound_ctrl:1
	v_add_f32_e32 v192, -1.0, v186
	v_fma_f32 v192, v10, v192, 1.0
	v_mul_f32_e32 v178, v210, v192
	v_add_f32_dpp v200, v200, v200 row_half_mirror row_mask:0xf bank_mask:0xf bound_ctrl:1
	v_add_f32_e32 v192, -1.0, v187
	v_fma_f32 v192, v11, v192, 1.0
	v_mul_f32_e32 v179, v211, v192
	v_add_f32_e32 v192, -1.0, v188
	v_fma_f32 v192, v12, v192, 1.0
	v_mul_f32_e32 v180, v212, v192
	v_add_f32_e32 v192, -1.0, v189
	v_fma_f32 v192, v13, v192, 1.0
	v_mul_f32_e32 v181, v213, v192
	v_add_f32_e32 v192, -1.0, v190
	v_fma_f32 v192, v14, v192, 1.0
	v_mul_f32_e32 v182, v214, v192
	v_add_f32_e32 v192, -1.0, v191
	v_fma_f32 v192, v15, v192, 1.0
	v_mul_f32_e32 v183, v215, v192
	v_max_f32_e32 v200, 0x179abe15, v200
	v_rsq_f32_e32 v201, v200
	v_mul_f32_e32 v192, v136, v176
	v_mul_f32_e32 v202, v16, v192
	v_mul_f32_e32 v160, v160, v201
	v_mul_f32_e32 v161, v161, v201
	v_mul_f32_e32 v162, v162, v201
	v_mul_f32_e32 v163, v163, v201
	v_mul_f32_e32 v164, v164, v201
	v_mul_f32_e32 v165, v165, v201
	v_mul_f32_e32 v166, v166, v201
	v_mul_f32_e32 v167, v167, v201
	v_mul_f32_e32 v168, v184, v160
	v_mul_f32_e32 v169, v185, v161
	v_mul_f32_e32 v170, v186, v162
	v_mul_f32_e32 v171, v187, v163
	v_mul_f32_e32 v172, v188, v164
	v_mul_f32_e32 v173, v189, v165
	v_mul_f32_e32 v174, v190, v166
	v_mul_f32_e32 v175, v191, v167
	ds_write_b128 v54, v[160:163] offset:20480
	ds_write_b128 v54, v[164:167] offset:20496
	ds_write_b128 v54, v[168:171] offset:20736
	ds_write_b128 v54, v[172:175] offset:20752
	v_mul_f32_e32 v192, v137, v177
	v_fmac_f32_e32 v202, v17, v192
	v_mul_f32_e32 v192, v138, v178
	v_fmac_f32_e32 v202, v18, v192
	v_mul_f32_e32 v192, v139, v179
	v_fmac_f32_e32 v202, v19, v192
	v_mul_f32_e32 v192, v140, v180
	v_fmac_f32_e32 v202, v20, v192
	v_mul_f32_e32 v192, v141, v181
	v_fmac_f32_e32 v202, v21, v192
	v_mul_f32_e32 v192, v142, v182
	v_fmac_f32_e32 v202, v22, v192
	v_mul_f32_e32 v192, v143, v183
	v_fmac_f32_e32 v202, v23, v192
	ds_write_b128 v54, v[176:179] offset:20992
	ds_write_b128 v54, v[180:183] offset:21008
	v_add_f32_dpp v202, v202, v202 quad_perm:[1,0,3,2] row_mask:0xf bank_mask:0xf bound_ctrl:1
	ds_write_b128 v54, v[136:139] offset:21248
	ds_write_b128 v54, v[140:143] offset:21264
	v_add_f32_dpp v202, v202, v202 quad_perm:[2,3,0,1] row_mask:0xf bank_mask:0xf bound_ctrl:1
	ds_write_b128 v54, v[152:155] offset:21504
	ds_write_b128 v54, v[156:159] offset:21520
	v_add_f32_dpp v202, v202, v202 row_half_mirror row_mask:0xf bank_mask:0xf bound_ctrl:1
	v_add_u32_e32 v205, s90, v56
	v_lshl_add_u32 v205, v205, 7, s64
	s_and_saveexec_b64 s[56:57], s[8:9]
	global_store_dword v205, v202, s[24:25]
	s_or_b64 exec, exec, s[56:57]
	v_add_u32_e32 v56, v59, v56
	s_waitcnt lgkmcnt(0)
	s_barrier
	s_waitcnt lgkmcnt(0)
	s_barrier

; template <int NS, bool LORA, int mat> ...
;     ...
;   const int ch = 64 * head + lane;
;   const float kk_c = p.k_k[ch], ka_c = p.k_a[ch], rk_c = p.r_k[ch];
;   const float mu_r = p.mu_shift[ch], mu_k = p.mu_shift[1024 + ch], mu_v = p.mu_shift[2048 + ch];
;   uint4 la[2][6];
;   u16 rv[2][NS][9];
; __device__ __forceinline__ void scan_run_job(const Params& p, float* lds, int job) {
;   if (job < 128) {
;     const int chain = job >> 2, q = job & 3;
;     scan_job<1, 2>(p, lds, 0, 16384, chain >> 1, chain & 1, q * 16, q);
.LBB0_1226:
	s_andn2_b64 vcc, exec, s[0:1]
	s_cbranch_vccnz .LBB0_1354
	s_ashr_i32 s0, s2, 3
	s_add_i32 s4, s3, s0
	s_and_b32 s3, s0, 3
	s_ashr_i32 s59, s4, 3
	s_bfe_u32 s58, s0, 0x10002
	s_cmp_eq_u32 s58, 0
	s_waitcnt vmcnt(7)
	v_mov_b32 v140, v146
	s_cselect_b64 s[0:1], -1, 0
	s_waitcnt vmcnt(0)
	v_ashrrev_i32_e32 v6, 6, v140
	v_and_b32_e32 v148, 63, v140
	v_cmp_lt_i32_e32 vcc, 3, v6
	s_and_saveexec_b64 s[6:7], vcc
	s_xor_b64 s[46:47], exec, s[6:7]
	s_cbranch_execz .LBB0_1346
	s_lshl_b32 s61, s59, 6
	s_lshl_b32 s63, s58, 6
	s_lshl_b32 s5, s58, 10
	s_ashr_i32 s6, s61, 31
	s_add_u32 s64, s61, s5
	s_addc_u32 s65, s6, 0
	s_add_i32 s62, s61, s5
	s_and_b32 s4, s4, -8
	s_lshl_b32 s5, s58, 2
	s_or_b32 s60, s5, s4
	v_cmp_lt_i32_e32 vcc, 4, v6
	s_and_saveexec_b64 s[4:5], vcc
	s_xor_b64 s[48:49], exec, s[4:5]
	s_cbranch_execz .LBB0_1319
	v_cmp_ne_u32_e32 vcc, 5, v6
	s_and_saveexec_b64 s[4:5], vcc
	s_xor_b64 s[52:53], exec, s[4:5]
	s_cbranch_execz .LBB0_1276
	v_readfirstlane_b32 s4, v6
	v_and_b32_e32 v48, 7, v148
	v_lshrrev_b32_e32 v49, 3, v148
	s_sub_i32 s4, s4, 6
	s_lshl_b32 s4, s4, 3
	v_add_u32_e32 v50, s4, v49
	v_lshl_add_u32 v51, v48, 3, s61
	v_lshlrev_b32_e32 v52, 1, v51
	v_add_u32_e32 v52, 0x800, v52
	v_lshlrev_b32_e32 v51, 2, v51
	v_mov_b32_e32 v53, 0x1c00
	v_mov_b32_e32 v58, 0x3fff
	v_mov_b32_e32 v59, -16
	v_cndmask_b32_e64 v59, v59, 16, s[0:1]
	v_add_u32_e32 v205, 0x1000, v51
	v_add_u32_e32 v206, 0x2000, v51
	global_load_dwordx4 v[0:3], v51, s[50:51]
	global_load_dwordx4 v[4:7], v51, s[50:51] offset:16
	global_load_dwordx4 v[8:11], v51, s[16:17]
	global_load_dwordx4 v[12:15], v51, s[16:17] offset:16
	global_load_dwordx4 v[16:19], v51, s[18:19]
	global_load_dwordx4 v[20:23], v51, s[18:19] offset:16
	global_load_dwordx4 v[24:27], v51, s[38:39]
	global_load_dwordx4 v[28:31], v51, s[38:39] offset:16
	global_load_dwordx4 v[32:35], v205, s[38:39]
	global_load_dwordx4 v[36:39], v205, s[38:39] offset:16
	global_load_dwordx4 v[40:43], v206, s[38:39]
	global_load_dwordx4 v[44:47], v206, s[38:39] offset:16
	v_mul_u32_u24_e32 v54, 0x500, v50
	v_lshlrev_b32_e32 v55, 8, v50
	v_lshl_add_u32 v54, v48, 5, v54
	v_lshl_add_u32 v55, v48, 5, v55
	v_add_u32_e32 v54, 0x5000, v54
	v_add_u32_e32 v55, 0x3000, v55
	v_sub_u32_e32 v205, v58, v50
	v_cndmask_b32_e64 v56, v205, v50, s[0:1]
	v_and_b32_e32 v205, 3, v50
	v_cmp_eq_u32_e64 s[8:9], s3, v205
	v_cmp_eq_u32_e32 vcc, 0, v48
	s_and_b64 s[8:9], s[8:9], vcc
	s_waitcnt vmcnt(0)
	v_cmp_lt_i32_e64 s[10:11], 0, v56
	v_cmp_gt_i32_e64 s[12:13], v58, v56
	v_mad_u32_u24 v205, v56, v53, v52
	s_nop 0
	v_cndmask_b32_e64 v206, 0, v53, s[10:11]
	v_cndmask_b32_e64 v207, 0, v53, s[12:13]
	v_cndmask_b32_e64 v60, 0, 1.0, s[10:11]
	v_cndmask_b32_e64 v61, 0, 1.0, s[12:13]
	v_sub_u32_e32 v206, v205, v206
	v_add_u32_e32 v207, v205, v207
	global_load_dwordx4 v[64:67], v205, s[72:73] offset:-2048
	global_load_dwordx4 v[68:71], v205, s[72:73]
	global_load_dwordx4 v[72:75], v205, s[72:73] offset:2048
	global_load_dwordx4 v[76:79], v206, s[72:73] offset:-2048
	global_load_dwordx4 v[80:83], v206, s[72:73]
	global_load_dwordx4 v[84:87], v206, s[72:73] offset:2048
	global_load_dwordx4 v[88:91], v207, s[72:73] offset:-2048
	global_load_dwordx4 v[92:95], v207, s[72:73]
	global_load_dwordx4 v[96:99], v207, s[72:73] offset:2048
	v_add_u32_e32 v57, v59, v56
	v_cmp_lt_i32_e64 s[10:11], 0, v57
	v_cmp_gt_i32_e64 s[12:13], v58, v57
	v_mad_u32_u24 v205, v57, v53, v52
	s_nop 0
	v_cndmask_b32_e64 v206, 0, v53, s[10:11]
	v_cndmask_b32_e64 v207, 0, v53, s[12:13]
	v_cndmask_b32_e64 v62, 0, 1.0, s[10:11]
	v_cndmask_b32_e64 v63, 0, 1.0, s[12:13]
	v_sub_u32_e32 v206, v205, v206
	v_add_u32_e32 v207, v205, v207
	global_load_dwordx4 v[100:103], v205, s[72:73] offset:-2048
	global_load_dwordx4 v[104:107], v205, s[72:73]
	global_load_dwordx4 v[108:111], v205, s[72:73] offset:2048
	global_load_dwordx4 v[112:115], v206, s[72:73] offset:-2048
	global_load_dwordx4 v[116:119], v206, s[72:73]
	global_load_dwordx4 v[120:123], v206, s[72:73] offset:2048
	global_load_dwordx4 v[124:127], v207, s[72:73] offset:-2048
	global_load_dwordx4 v[128:131], v207, s[72:73]
	global_load_dwordx4 v[132:135], v207, s[72:73] offset:2048
	s_mov_b32 s66, 3
	s_waitcnt lgkmcnt(0)
	s_barrier
	ds_read_b128 v[184:187], v55 offset:0
	ds_read_b128 v[188:191], v55 offset:16
	s_waitcnt vmcnt(9)
	v_lshlrev_b32_e32 v136, 16, v64
	v_lshlrev_b32_e32 v192, 16, v76
	v_lshlrev_b32_e32 v193, 16, v88
	v_mul_f32_e32 v193, v61, v193
	v_fmac_f32_e32 v193, v60, v192
	v_fma_f32 v192, v193, 0.5, -v136
	v_fmac_f32_e32 v136, v24, v192
	v_and_b32_e32 v137, 0xffff0000, v64
	v_and_b32_e32 v192, 0xffff0000, v76
	v_and_b32_e32 v193, 0xffff0000, v88
	v_mul_f32_e32 v193, v61, v193
	v_fmac_f32_e32 v193, v60, v192
	v_fma_f32 v192, v193, 0.5, -v137
	v_fmac_f32_e32 v137, v25, v192
	v_lshlrev_b32_e32 v138, 16, v65
	v_lshlrev_b32_e32 v192, 16, v77
	v_lshlrev_b32_e32 v193, 16, v89
	v_mul_f32_e32 v193, v61, v193
	v_fmac_f32_e32 v193, v60, v192
	v_fma_f32 v192, v193, 0.5, -v138
	v_fmac_f32_e32 v138, v26, v192
	v_and_b32_e32 v139, 0xffff0000, v65
	v_and_b32_e32 v192, 0xffff0000, v77
	v_and_b32_e32 v193, 0xffff0000, v89
	v_mul_f32_e32 v193, v61, v193
	v_fmac_f32_e32 v193, v60, v192
	v_fma_f32 v192, v193, 0.5, -v139
	v_fmac_f32_e32 v139, v27, v192
	v_lshlrev_b32_e32 v140, 16, v66
	v_lshlrev_b32_e32 v192, 16, v78
	v_lshlrev_b32_e32 v193, 16, v90
	v_mul_f32_e32 v193, v61, v193
	v_fmac_f32_e32 v193, v60, v192
	v_fma_f32 v192, v193, 0.5, -v140
	v_fmac_f32_e32 v140, v28, v192
	v_and_b32_e32 v141, 0xffff0000, v66
	v_and_b32_e32 v192, 0xffff0000, v78
	v_and_b32_e32 v193, 0xffff0000, v90
	v_mul_f32_e32 v193, v61, v193
	v_fmac_f32_e32 v193, v60, v192
	v_fma_f32 v192, v193, 0.5, -v141
	v_fmac_f32_e32 v141, v29, v192
	v_lshlrev_b32_e32 v142, 16, v67
	v_lshlrev_b32_e32 v192, 16, v79
	v_lshlrev_b32_e32 v193, 16, v91
	v_mul_f32_e32 v193, v61, v193
	v_fmac_f32_e32 v193, v60, v192
	v_fma_f32 v192, v193, 0.5, -v142
	v_fmac_f32_e32 v142, v30, v192
	v_and_b32_e32 v143, 0xffff0000, v67
	v_and_b32_e32 v192, 0xffff0000, v79
	v_and_b32_e32 v193, 0xffff0000, v91
	v_mul_f32_e32 v193, v61, v193
	v_fmac_f32_e32 v193, v60, v192
	v_fma_f32 v192, v193, 0.5, -v143
	v_fmac_f32_e32 v143, v31, v192
	v_lshlrev_b32_e32 v208, 16, v68
	v_lshlrev_b32_e32 v192, 16, v80
	v_lshlrev_b32_e32 v193, 16, v92
	v_mul_f32_e32 v193, v61, v193
	v_fmac_f32_e32 v193, v60, v192
	v_fma_f32 v192, v193, 0.5, -v208
	v_fmac_f32_e32 v208, v32, v192
	v_and_b32_e32 v209, 0xffff0000, v68
	v_and_b32_e32 v192, 0xffff0000, v80
	v_and_b32_e32 v193, 0xffff0000, v92
	v_mul_f32_e32 v193, v61, v193
	v_fmac_f32_e32 v193, v60, v192
	v_fma_f32 v192, v193, 0.5, -v209
	v_fmac_f32_e32 v209, v33, v192
	v_lshlrev_b32_e32 v210, 16, v69
	v_lshlrev_b32_e32 v192, 16, v81
	v_lshlrev_b32_e32 v193, 16, v93
	v_mul_f32_e32 v193, v61, v193
	v_fmac_f32_e32 v193, v60, v192
	v_fma_f32 v192, v193, 0.5, -v210
	v_fmac_f32_e32 v210, v34, v192
	v_and_b32_e32 v211, 0xffff0000, v69
	v_and_b32_e32 v192, 0xffff0000, v81
	v_and_b32_e32 v193, 0xffff0000, v93
	v_mul_f32_e32 v193, v61, v193
	v_fmac_f32_e32 v193, v60, v192
	v_fma_f32 v192, v193, 0.5, -v211
	v_fmac_f32_e32 v211, v35, v192
	v_lshlrev_b32_e32 v212, 16, v70
	v_lshlrev_b32_e32 v192, 16, v82
	v_lshlrev_b32_e32 v193, 16, v94
	v_mul_f32_e32 v193, v61, v193
	v_fmac_f32_e32 v193, v60, v192
	v_fma_f32 v192, v193, 0.5, -v212
	v_fmac_f32_e32 v212, v36, v192
	v_and_b32_e32 v213, 0xffff0000, v70
	v_and_b32_e32 v192, 0xffff0000, v82
	v_and_b32_e32 v193, 0xffff0000, v94
	v_mul_f32_e32 v193, v61, v193
	v_fmac_f32_e32 v193, v60, v192
	v_fma_f32 v192, v193, 0.5, -v213
	v_fmac_f32_e32 v213, v37, v192
	v_lshlrev_b32_e32 v214, 16, v71
	v_lshlrev_b32_e32 v192, 16, v83
	v_lshlrev_b32_e32 v193, 16, v95
	v_mul_f32_e32 v193, v61, v193
	v_fmac_f32_e32 v193, v60, v192
	v_fma_f32 v192, v193, 0.5, -v214
	v_fmac_f32_e32 v214, v38, v192
	v_and_b32_e32 v215, 0xffff0000, v71
	v_and_b32_e32 v192, 0xffff0000, v83
	v_and_b32_e32 v193, 0xffff0000, v95
	v_mul_f32_e32 v193, v61, v193
	v_fmac_f32_e32 v193, v60, v192
	v_fma_f32 v192, v193, 0.5, -v215
	v_fmac_f32_e32 v215, v39, v192
	v_lshlrev_b32_e32 v152, 16, v72
	v_lshlrev_b32_e32 v192, 16, v84
	v_lshlrev_b32_e32 v193, 16, v96
	v_mul_f32_e32 v193, v61, v193
	v_fmac_f32_e32 v193, v60, v192
	v_fma_f32 v192, v193, 0.5, -v152
	v_fmac_f32_e32 v152, v40, v192
	v_and_b32_e32 v153, 0xffff0000, v72
	v_and_b32_e32 v192, 0xffff0000, v84
	v_and_b32_e32 v193, 0xffff0000, v96
	v_mul_f32_e32 v193, v61, v193
	v_fmac_f32_e32 v193, v60, v192
	v_fma_f32 v192, v193, 0.5, -v153
	v_fmac_f32_e32 v153, v41, v192
	v_lshlrev_b32_e32 v154, 16, v73
	v_lshlrev_b32_e32 v192, 16, v85
	v_lshlrev_b32_e32 v193, 16, v97
	v_mul_f32_e32 v193, v61, v193
	v_fmac_f32_e32 v193, v60, v192
	v_fma_f32 v192, v193, 0.5, -v154
	v_fmac_f32_e32 v154, v42, v192
	v_and_b32_e32 v155, 0xffff0000, v73
	v_and_b32_e32 v192, 0xffff0000, v85
	v_and_b32_e32 v193, 0xffff0000, v97
	v_mul_f32_e32 v193, v61, v193
	v_fmac_f32_e32 v193, v60, v192
	v_fma_f32 v192, v193, 0.5, -v155
	v_fmac_f32_e32 v155, v43, v192
	v_lshlrev_b32_e32 v156, 16, v74
	v_lshlrev_b32_e32 v192, 16, v86
	v_lshlrev_b32_e32 v193, 16, v98
	v_mul_f32_e32 v193, v61, v193
	v_fmac_f32_e32 v193, v60, v192
	v_fma_f32 v192, v193, 0.5, -v156
	v_fmac_f32_e32 v156, v44, v192
	v_and_b32_e32 v157, 0xffff0000, v74
	v_and_b32_e32 v192, 0xffff0000, v86
	v_and_b32_e32 v193, 0xffff0000, v98
	v_mul_f32_e32 v193, v61, v193
	v_fmac_f32_e32 v193, v60, v192
	v_fma_f32 v192, v193, 0.5, -v157
	v_fmac_f32_e32 v157, v45, v192
	v_lshlrev_b32_e32 v158, 16, v75
	v_lshlrev_b32_e32 v192, 16, v87
	v_lshlrev_b32_e32 v193, 16, v99
	v_mul_f32_e32 v193, v61, v193
	v_fmac_f32_e32 v193, v60, v192
	v_fma_f32 v192, v193, 0.5, -v158
	v_fmac_f32_e32 v158, v46, v192
	v_and_b32_e32 v159, 0xffff0000, v75
	v_and_b32_e32 v192, 0xffff0000, v87
	v_and_b32_e32 v193, 0xffff0000, v99
	v_mul_f32_e32 v193, v61, v193
	v_fmac_f32_e32 v193, v60, v192
	v_fma_f32 v192, v193, 0.5, -v159
	v_fmac_f32_e32 v159, v47, v192
	v_add_u32_e32 v57, v59, v56
	v_add_u32_e32 v57, v59, v57
	v_cmp_lt_i32_e64 s[10:11], 0, v57
	v_cmp_gt_i32_e64 s[12:13], v58, v57
	v_mad_u32_u24 v205, v57, v53, v52
	s_nop 0
	v_cndmask_b32_e64 v206, 0, v53, s[10:11]
	v_cndmask_b32_e64 v207, 0, v53, s[12:13]
	v_cndmask_b32_e64 v60, 0, 1.0, s[10:11]
	v_cndmask_b32_e64 v61, 0, 1.0, s[12:13]
	v_sub_u32_e32 v206, v205, v206
	v_add_u32_e32 v207, v205, v207
	global_load_dwordx4 v[64:67], v205, s[72:73] offset:-2048
	global_load_dwordx4 v[68:71], v205, s[72:73]
	global_load_dwordx4 v[72:75], v205, s[72:73] offset:2048
	global_load_dwordx4 v[76:79], v206, s[72:73] offset:-2048
	global_load_dwordx4 v[80:83], v206, s[72:73]
	global_load_dwordx4 v[84:87], v206, s[72:73] offset:2048
	global_load_dwordx4 v[88:91], v207, s[72:73] offset:-2048
	global_load_dwordx4 v[92:95], v207, s[72:73]
	global_load_dwordx4 v[96:99], v207, s[72:73] offset:2048
	v_mul_f32_e32 v160, v0, v208
	v_mul_f32_e32 v161, v1, v209
	v_mul_f32_e32 v162, v2, v210
	v_mul_f32_e32 v163, v3, v211
	v_mul_f32_e32 v164, v4, v212
	v_mul_f32_e32 v165, v5, v213
	v_mul_f32_e32 v166, v6, v214
	v_mul_f32_e32 v167, v7, v215
	v_mul_f32_e32 v200, v160, v160
	v_fmac_f32_e32 v200, v161, v161
	v_fmac_f32_e32 v200, v162, v162
	v_fmac_f32_e32 v200, v163, v163
	v_fmac_f32_e32 v200, v164, v164
	v_fmac_f32_e32 v200, v165, v165
	v_fmac_f32_e32 v200, v166, v166
	v_fmac_f32_e32 v200, v167, v167
	s_waitcnt lgkmcnt(0)
	v_add_f32_e32 v192, -1.0, v184
	v_fma_f32 v192, v8, v192, 1.0
	v_mul_f32_e32 v176, v208, v192
	v_add_f32_dpp v200, v200, v200 quad_perm:[1,0,3,2] row_mask:0xf bank_mask:0xf bound_ctrl:1
	v_add_f32_e32 v192, -1.0, v185
	v_fma_f32 v192, v9, v192, 1.0
	v_mul_f32_e32 v177, v209, v192
	v_add_f32_dpp v200, v200, v200 quad_perm:[2,3,0,1] row_mask:0xf bank_mask:0xf bound_ctrl:1
	v_add_f32_e32 v192, -1.0, v186
	v_fma_f32 v192, v10, v192, 1.0
	v_mul_f32_e32 v178, v210, v192
	v_add_f32_dpp v200, v200, v200 row_half_mirror row_mask:0xf bank_mask:0xf bound_ctrl:1
	v_add_f32_e32 v192, -1.0, v187
	v_fma_f32 v192, v11, v192, 1.0
	v_mul_f32_e32 v179, v211, v192
	v_add_f32_e32 v192, -1.0, v188
	v_fma_f32 v192, v12, v192, 1.0
	v_mul_f32_e32 v180, v212, v192
	v_add_f32_e32 v192, -1.0, v189
	v_fma_f32 v192, v13, v192, 1.0
	v_mul_f32_e32 v181, v213, v192
	v_add_f32_e32 v192, -1.0, v190
	v_fma_f32 v192, v14, v192, 1.0
	v_mul_f32_e32 v182, v214, v192
	v_add_f32_e32 v192, -1.0, v191
	v_fma_f32 v192, v15, v192, 1.0
	v_mul_f32_e32 v183, v215, v192
	v_max_f32_e32 v200, 0x179abe15, v200
	v_rsq_f32_e32 v201, v200
	v_mul_f32_e32 v192, v136, v176
	v_mul_f32_e32 v202, v16, v192
	v_mul_f32_e32 v160, v160, v201
	v_mul_f32_e32 v161, v161, v201
	v_mul_f32_e32 v162, v162, v201
	v_mul_f32_e32 v163, v163, v201
	v_mul_f32_e32 v164, v164, v201
	v_mul_f32_e32 v165, v165, v201
	v_mul_f32_e32 v166, v166, v201
	v_mul_f32_e32 v167, v167, v201
	v_mul_f32_e32 v168, v184, v160
	v_mul_f32_e32 v169, v185, v161
	v_mul_f32_e32 v170, v186, v162
	v_mul_f32_e32 v171, v187, v163
	v_mul_f32_e32 v172, v188, v164
	v_mul_f32_e32 v173, v189, v165
	v_mul_f32_e32 v174, v190, v166
	v_mul_f32_e32 v175, v191, v167
	ds_write_b128 v54, v[160:163] offset:0
	ds_write_b128 v54, v[164:167] offset:16
	ds_write_b128 v54, v[168:171] offset:256
	ds_write_b128 v54, v[172:175] offset:272
	v_mul_f32_e32 v192, v137, v177
	v_fmac_f32_e32 v202, v17, v192
	v_mul_f32_e32 v192, v138, v178
	v_fmac_f32_e32 v202, v18, v192
	v_mul_f32_e32 v192, v139, v179
	v_fmac_f32_e32 v202, v19, v192
	v_mul_f32_e32 v192, v140, v180
	v_fmac_f32_e32 v202, v20, v192
	v_mul_f32_e32 v192, v141, v181
	v_fmac_f32_e32 v202, v21, v192
	v_mul_f32_e32 v192, v142, v182
	v_fmac_f32_e32 v202, v22, v192
	v_mul_f32_e32 v192, v143, v183
	v_fmac_f32_e32 v202, v23, v192
	ds_write_b128 v54, v[176:179] offset:512
	ds_write_b128 v54, v[180:183] offset:528
	v_add_f32_dpp v202, v202, v202 quad_perm:[1,0,3,2] row_mask:0xf bank_mask:0xf bound_ctrl:1
	ds_write_b128 v54, v[136:139] offset:768
	ds_write_b128 v54, v[140:143] offset:784
	v_add_f32_dpp v202, v202, v202 quad_perm:[2,3,0,1] row_mask:0xf bank_mask:0xf bound_ctrl:1
	ds_write_b128 v54, v[152:155] offset:1024
	ds_write_b128 v54, v[156:159] offset:1040
	v_add_f32_dpp v202, v202, v202 row_half_mirror row_mask:0xf bank_mask:0xf bound_ctrl:1
	v_lshl_add_u32 v205, v56, 7, s60
	s_and_saveexec_b64 s[6:7], s[8:9]
	global_store_dword v205, v202, s[24:25]
	s_or_b64 exec, exec, s[6:7]
	v_add_u32_e32 v56, v59, v56
	s_waitcnt lgkmcnt(0)
	s_barrier
	ds_read_b128 v[184:187], v55 offset:4096
	ds_read_b128 v[188:191], v55 offset:4112
	s_waitcnt vmcnt(9)
	v_lshlrev_b32_e32 v136, 16, v100
	v_lshlrev_b32_e32 v192, 16, v112
	v_lshlrev_b32_e32 v193, 16, v124
	v_mul_f32_e32 v193, v63, v193
	v_fmac_f32_e32 v193, v62, v192
	v_fma_f32 v192, v193, 0.5, -v136
	v_fmac_f32_e32 v136, v24, v192
	v_and_b32_e32 v137, 0xffff0000, v100
	v_and_b32_e32 v192, 0xffff0000, v112
	v_and_b32_e32 v193, 0xffff0000, v124
	v_mul_f32_e32 v193, v63, v193
	v_fmac_f32_e32 v193, v62, v192
	v_fma_f32 v192, v193, 0.5, -v137
	v_fmac_f32_e32 v137, v25, v192
	v_lshlrev_b32_e32 v138, 16, v101
	v_lshlrev_b32_e32 v192, 16, v113
	v_lshlrev_b32_e32 v193, 16, v125
	v_mul_f32_e32 v193, v63, v193
	v_fmac_f32_e32 v193, v62, v192
	v_fma_f32 v192, v193, 0.5, -v138
	v_fmac_f32_e32 v138, v26, v192
	v_and_b32_e32 v139, 0xffff0000, v101
	v_and_b32_e32 v192, 0xffff0000, v113
	v_and_b32_e32 v193, 0xffff0000, v125
	v_mul_f32_e32 v193, v63, v193
	v_fmac_f32_e32 v193, v62, v192
	v_fma_f32 v192, v193, 0.5, -v139
	v_fmac_f32_e32 v139, v27, v192
	v_lshlrev_b32_e32 v140, 16, v102
	v_lshlrev_b32_e32 v192, 16, v114
	v_lshlrev_b32_e32 v193, 16, v126
	v_mul_f32_e32 v193, v63, v193
	v_fmac_f32_e32 v193, v62, v192
	v_fma_f32 v192, v193, 0.5, -v140
	v_fmac_f32_e32 v140, v28, v192
	v_and_b32_e32 v141, 0xffff0000, v102
	v_and_b32_e32 v192, 0xffff0000, v114
	v_and_b32_e32 v193, 0xffff0000, v126
	v_mul_f32_e32 v193, v63, v193
	v_fmac_f32_e32 v193, v62, v192
	v_fma_f32 v192, v193, 0.5, -v141
	v_fmac_f32_e32 v141, v29, v192
	v_lshlrev_b32_e32 v142, 16, v103
	v_lshlrev_b32_e32 v192, 16, v115
	v_lshlrev_b32_e32 v193, 16, v127
	v_mul_f32_e32 v193, v63, v193
	v_fmac_f32_e32 v193, v62, v192
	v_fma_f32 v192, v193, 0.5, -v142
	v_fmac_f32_e32 v142, v30, v192
	v_and_b32_e32 v143, 0xffff0000, v103
	v_and_b32_e32 v192, 0xffff0000, v115
	v_and_b32_e32 v193, 0xffff0000, v127
	v_mul_f32_e32 v193, v63, v193
	v_fmac_f32_e32 v193, v62, v192
	v_fma_f32 v192, v193, 0.5, -v143
	v_fmac_f32_e32 v143, v31, v192
	v_lshlrev_b32_e32 v208, 16, v104
	v_lshlrev_b32_e32 v192, 16, v116
	v_lshlrev_b32_e32 v193, 16, v128
	v_mul_f32_e32 v193, v63, v193
	v_fmac_f32_e32 v193, v62, v192
	v_fma_f32 v192, v193, 0.5, -v208
	v_fmac_f32_e32 v208, v32, v192
	v_and_b32_e32 v209, 0xffff0000, v104
	v_and_b32_e32 v192, 0xffff0000, v116
	v_and_b32_e32 v193, 0xffff0000, v128
	v_mul_f32_e32 v193, v63, v193
	v_fmac_f32_e32 v193, v62, v192
	v_fma_f32 v192, v193, 0.5, -v209
	v_fmac_f32_e32 v209, v33, v192
	v_lshlrev_b32_e32 v210, 16, v105
	v_lshlrev_b32_e32 v192, 16, v117
	v_lshlrev_b32_e32 v193, 16, v129
	v_mul_f32_e32 v193, v63, v193
	v_fmac_f32_e32 v193, v62, v192
	v_fma_f32 v192, v193, 0.5, -v210
	v_fmac_f32_e32 v210, v34, v192
	v_and_b32_e32 v211, 0xffff0000, v105
	v_and_b32_e32 v192, 0xffff0000, v117
	v_and_b32_e32 v193, 0xffff0000, v129
	v_mul_f32_e32 v193, v63, v193
	v_fmac_f32_e32 v193, v62, v192
	v_fma_f32 v192, v193, 0.5, -v211
	v_fmac_f32_e32 v211, v35, v192
	v_lshlrev_b32_e32 v212, 16, v106
	v_lshlrev_b32_e32 v192, 16, v118
	v_lshlrev_b32_e32 v193, 16, v130
	v_mul_f32_e32 v193, v63, v193
	v_fmac_f32_e32 v193, v62, v192
	v_fma_f32 v192, v193, 0.5, -v212
	v_fmac_f32_e32 v212, v36, v192
	v_and_b32_e32 v213, 0xffff0000, v106
	v_and_b32_e32 v192, 0xffff0000, v118
	v_and_b32_e32 v193, 0xffff0000, v130
	v_mul_f32_e32 v193, v63, v193
	v_fmac_f32_e32 v193, v62, v192
	v_fma_f32 v192, v193, 0.5, -v213
	v_fmac_f32_e32 v213, v37, v192
	v_lshlrev_b32_e32 v214, 16, v107
	v_lshlrev_b32_e32 v192, 16, v119
	v_lshlrev_b32_e32 v193, 16, v131
	v_mul_f32_e32 v193, v63, v193
	v_fmac_f32_e32 v193, v62, v192
	v_fma_f32 v192, v193, 0.5, -v214
	v_fmac_f32_e32 v214, v38, v192
	v_and_b32_e32 v215, 0xffff0000, v107
	v_and_b32_e32 v192, 0xffff0000, v119
	v_and_b32_e32 v193, 0xffff0000, v131
	v_mul_f32_e32 v193, v63, v193
	v_fmac_f32_e32 v193, v62, v192
	v_fma_f32 v192, v193, 0.5, -v215
	v_fmac_f32_e32 v215, v39, v192
	v_lshlrev_b32_e32 v152, 16, v108
	v_lshlrev_b32_e32 v192, 16, v120
	v_lshlrev_b32_e32 v193, 16, v132
	v_mul_f32_e32 v193, v63, v193
	v_fmac_f32_e32 v193, v62, v192
	v_fma_f32 v192, v193, 0.5, -v152
	v_fmac_f32_e32 v152, v40, v192
	v_and_b32_e32 v153, 0xffff0000, v108
	v_and_b32_e32 v192, 0xffff0000, v120
	v_and_b32_e32 v193, 0xffff0000, v132
	v_mul_f32_e32 v193, v63, v193
	v_fmac_f32_e32 v193, v62, v192
	v_fma_f32 v192, v193, 0.5, -v153
	v_fmac_f32_e32 v153, v41, v192
	v_lshlrev_b32_e32 v154, 16, v109
	v_lshlrev_b32_e32 v192, 16, v121
	v_lshlrev_b32_e32 v193, 16, v133
	v_mul_f32_e32 v193, v63, v193
	v_fmac_f32_e32 v193, v62, v192
	v_fma_f32 v192, v193, 0.5, -v154
	v_fmac_f32_e32 v154, v42, v192
	v_and_b32_e32 v155, 0xffff0000, v109
	v_and_b32_e32 v192, 0xffff0000, v121
	v_and_b32_e32 v193, 0xffff0000, v133
	v_mul_f32_e32 v193, v63, v193
	v_fmac_f32_e32 v193, v62, v192
	v_fma_f32 v192, v193, 0.5, -v155
	v_fmac_f32_e32 v155, v43, v192
	v_lshlrev_b32_e32 v156, 16, v110
	v_lshlrev_b32_e32 v192, 16, v122
	v_lshlrev_b32_e32 v193, 16, v134
	v_mul_f32_e32 v193, v63, v193
	v_fmac_f32_e32 v193, v62, v192
	v_fma_f32 v192, v193, 0.5, -v156
	v_fmac_f32_e32 v156, v44, v192
	v_and_b32_e32 v157, 0xffff0000, v110
	v_and_b32_e32 v192, 0xffff0000, v122
	v_and_b32_e32 v193, 0xffff0000, v134
	v_mul_f32_e32 v193, v63, v193
	v_fmac_f32_e32 v193, v62, v192
	v_fma_f32 v192, v193, 0.5, -v157
	v_fmac_f32_e32 v157, v45, v192
	v_lshlrev_b32_e32 v158, 16, v111
	v_lshlrev_b32_e32 v192, 16, v123
	v_lshlrev_b32_e32 v193, 16, v135
	v_mul_f32_e32 v193, v63, v193
	v_fmac_f32_e32 v193, v62, v192
	v_fma_f32 v192, v193, 0.5, -v158
	v_fmac_f32_e32 v158, v46, v192
	v_and_b32_e32 v159, 0xffff0000, v111
	v_and_b32_e32 v192, 0xffff0000, v123
	v_and_b32_e32 v193, 0xffff0000, v135
	v_mul_f32_e32 v193, v63, v193
	v_fmac_f32_e32 v193, v62, v192
	v_fma_f32 v192, v193, 0.5, -v159
	v_fmac_f32_e32 v159, v47, v192
	v_add_u32_e32 v57, v59, v56
	v_add_u32_e32 v57, v59, v57
	v_cmp_lt_i32_e64 s[10:11], 0, v57
	v_cmp_gt_i32_e64 s[12:13], v58, v57
	v_mad_u32_u24 v205, v57, v53, v52
	s_nop 0
	v_cndmask_b32_e64 v206, 0, v53, s[10:11]
	v_cndmask_b32_e64 v207, 0, v53, s[12:13]
	v_cndmask_b32_e64 v62, 0, 1.0, s[10:11]
	v_cndmask_b32_e64 v63, 0, 1.0, s[12:13]
	v_sub_u32_e32 v206, v205, v206
	v_add_u32_e32 v207, v205, v207
	global_load_dwordx4 v[100:103], v205, s[72:73] offset:-2048
	global_load_dwordx4 v[104:107], v205, s[72:73]
	global_load_dwordx4 v[108:111], v205, s[72:73] offset:2048
	global_load_dwordx4 v[112:115], v206, s[72:73] offset:-2048
	global_load_dwordx4 v[116:119], v206, s[72:73]
	global_load_dwordx4 v[120:123], v206, s[72:73] offset:2048
	global_load_dwordx4 v[124:127], v207, s[72:73] offset:-2048
	global_load_dwordx4 v[128:131], v207, s[72:73]
	global_load_dwordx4 v[132:135], v207, s[72:73] offset:2048
	v_mul_f32_e32 v160, v0, v208
	v_mul_f32_e32 v161, v1, v209
	v_mul_f32_e32 v162, v2, v210
	v_mul_f32_e32 v163, v3, v211
	v_mul_f32_e32 v164, v4, v212
	v_mul_f32_e32 v165, v5, v213
	v_mul_f32_e32 v166, v6, v214
	v_mul_f32_e32 v167, v7, v215
	v_mul_f32_e32 v200, v160, v160
	v_fmac_f32_e32 v200, v161, v161
	v_fmac_f32_e32 v200, v162, v162
	v_fmac_f32_e32 v200, v163, v163
	v_fmac_f32_e32 v200, v164, v164
	v_fmac_f32_e32 v200, v165, v165
	v_fmac_f32_e32 v200, v166, v166
	v_fmac_f32_e32 v200, v167, v167
	s_waitcnt lgkmcnt(0)
	v_add_f32_e32 v192, -1.0, v184
	v_fma_f32 v192, v8, v192, 1.0
	v_mul_f32_e32 v176, v208, v192
	v_add_f32_dpp v200, v200, v200 quad_perm:[1,0,3,2] row_mask:0xf bank_mask:0xf bound_ctrl:1
	v_add_f32_e32 v192, -1.0, v185
	v_fma_f32 v192, v9, v192, 1.0
	v_mul_f32_e32 v177, v209, v192
	v_add_f32_dpp v200, v200, v200 quad_perm:[2,3,0,1] row_mask:0xf bank_mask:0xf bound_ctrl:1
	v_add_f32_e32 v192, -1.0, v186
	v_fma_f32 v192, v10, v192, 1.0
	v_mul_f32_e32 v178, v210, v192
	v_add_f32_dpp v200, v200, v200 row_half_mirror row_mask:0xf bank_mask:0xf bound_ctrl:1
	v_add_f32_e32 v192, -1.0, v187
	v_fma_f32 v192, v11, v192, 1.0
	v_mul_f32_e32 v179, v211, v192
	v_add_f32_e32 v192, -1.0, v188
	v_fma_f32 v192, v12, v192, 1.0
	v_mul_f32_e32 v180, v212, v192
	v_add_f32_e32 v192, -1.0, v189
	v_fma_f32 v192, v13, v192, 1.0
	v_mul_f32_e32 v181, v213, v192
	v_add_f32_e32 v192, -1.0, v190
	v_fma_f32 v192, v14, v192, 1.0
	v_mul_f32_e32 v182, v214, v192
	v_add_f32_e32 v192, -1.0, v191
	v_fma_f32 v192, v15, v192, 1.0
	v_mul_f32_e32 v183, v215, v192
	v_max_f32_e32 v200, 0x179abe15, v200
	v_rsq_f32_e32 v201, v200
	v_mul_f32_e32 v192, v136, v176
	v_mul_f32_e32 v202, v16, v192
	v_mul_f32_e32 v160, v160, v201
	v_mul_f32_e32 v161, v161, v201
	v_mul_f32_e32 v162, v162, v201
	v_mul_f32_e32 v163, v163, v201
	v_mul_f32_e32 v164, v164, v201
	v_mul_f32_e32 v165, v165, v201
	v_mul_f32_e32 v166, v166, v201
	v_mul_f32_e32 v167, v167, v201
	v_mul_f32_e32 v168, v184, v160
	v_mul_f32_e32 v169, v185, v161
	v_mul_f32_e32 v170, v186, v162
	v_mul_f32_e32 v171, v187, v163
	v_mul_f32_e32 v172, v188, v164
	v_mul_f32_e32 v173, v189, v165
	v_mul_f32_e32 v174, v190, v166
	v_mul_f32_e32 v175, v191, v167
	ds_write_b128 v54, v[160:163] offset:20480
	ds_write_b128 v54, v[164:167] offset:20496
	ds_write_b128 v54, v[168:171] offset:20736
	ds_write_b128 v54, v[172:175] offset:20752
	v_mul_f32_e32 v192, v137, v177
	v_fmac_f32_e32 v202, v17, v192
	v_mul_f32_e32 v192, v138, v178
	v_fmac_f32_e32 v202, v18, v192
	v_mul_f32_e32 v192, v139, v179
	v_fmac_f32_e32 v202, v19, v192
	v_mul_f32_e32 v192, v140, v180
	v_fmac_f32_e32 v202, v20, v192
	v_mul_f32_e32 v192, v141, v181
	v_fmac_f32_e32 v202, v21, v192
	v_mul_f32_e32 v192, v142, v182
	v_fmac_f32_e32 v202, v22, v192
	v_mul_f32_e32 v192, v143, v183
	v_fmac_f32_e32 v202, v23, v192
	ds_write_b128 v54, v[176:179] offset:20992
	ds_write_b128 v54, v[180:183] offset:21008
	v_add_f32_dpp v202, v202, v202 quad_perm:[1,0,3,2] row_mask:0xf bank_mask:0xf bound_ctrl:1
	ds_write_b128 v54, v[136:139] offset:21248
	ds_write_b128 v54, v[140:143] offset:21264
	v_add_f32_dpp v202, v202, v202 quad_perm:[2,3,0,1] row_mask:0xf bank_mask:0xf bound_ctrl:1
	ds_write_b128 v54, v[152:155] offset:21504
	ds_write_b128 v54, v[156:159] offset:21520
	v_add_f32_dpp v202, v202, v202 row_half_mirror row_mask:0xf bank_mask:0xf bound_ctrl:1
	v_lshl_add_u32 v205, v56, 7, s60
	s_and_saveexec_b64 s[6:7], s[8:9]
	global_store_dword v205, v202, s[24:25]
	s_or_b64 exec, exec, s[6:7]
	v_add_u32_e32 v56, v59, v56
	s_waitcnt lgkmcnt(0)
	s_barrier
.Lmy_kp_loop:
	ds_read_b128 v[184:187], v55 offset:0
	ds_read_b128 v[188:191], v55 offset:16
	s_waitcnt vmcnt(9)
	v_lshlrev_b32_e32 v136, 16, v64
	v_lshlrev_b32_e32 v192, 16, v76
	v_lshlrev_b32_e32 v193, 16, v88
	v_add_f32_e32 v193, v193, v192
	v_fma_f32 v192, v193, 0.5, -v136
	v_fmac_f32_e32 v136, v24, v192
	v_and_b32_e32 v137, 0xffff0000, v64
	v_and_b32_e32 v192, 0xffff0000, v76
	v_and_b32_e32 v193, 0xffff0000, v88
	v_add_f32_e32 v193, v193, v192
	v_fma_f32 v192, v193, 0.5, -v137
	v_fmac_f32_e32 v137, v25, v192
	v_lshlrev_b32_e32 v138, 16, v65
	v_lshlrev_b32_e32 v192, 16, v77
	v_lshlrev_b32_e32 v193, 16, v89
	v_add_f32_e32 v193, v193, v192
	v_fma_f32 v192, v193, 0.5, -v138
	v_fmac_f32_e32 v138, v26, v192
	v_and_b32_e32 v139, 0xffff0000, v65
	v_and_b32_e32 v192, 0xffff0000, v77
	v_and_b32_e32 v193, 0xffff0000, v89
	v_add_f32_e32 v193, v193, v192
	v_fma_f32 v192, v193, 0.5, -v139
	v_fmac_f32_e32 v139, v27, v192
	v_lshlrev_b32_e32 v140, 16, v66
	v_lshlrev_b32_e32 v192, 16, v78
	v_lshlrev_b32_e32 v193, 16, v90
	v_add_f32_e32 v193, v193, v192
	v_fma_f32 v192, v193, 0.5, -v140
	v_fmac_f32_e32 v140, v28, v192
	v_and_b32_e32 v141, 0xffff0000, v66
	v_and_b32_e32 v192, 0xffff0000, v78
	v_and_b32_e32 v193, 0xffff0000, v90
	v_add_f32_e32 v193, v193, v192
	v_fma_f32 v192, v193, 0.5, -v141
	v_fmac_f32_e32 v141, v29, v192
	v_lshlrev_b32_e32 v142, 16, v67
	v_lshlrev_b32_e32 v192, 16, v79
	v_lshlrev_b32_e32 v193, 16, v91
	v_add_f32_e32 v193, v193, v192
	v_fma_f32 v192, v193, 0.5, -v142
	v_fmac_f32_e32 v142, v30, v192
	v_and_b32_e32 v143, 0xffff0000, v67
	v_and_b32_e32 v192, 0xffff0000, v79
	v_and_b32_e32 v193, 0xffff0000, v91
	v_add_f32_e32 v193, v193, v192
	v_fma_f32 v192, v193, 0.5, -v143
	v_fmac_f32_e32 v143, v31, v192
	v_lshlrev_b32_e32 v208, 16, v68
	v_lshlrev_b32_e32 v192, 16, v80
	v_lshlrev_b32_e32 v193, 16, v92
	v_add_f32_e32 v193, v193, v192
	v_fma_f32 v192, v193, 0.5, -v208
	v_fmac_f32_e32 v208, v32, v192
	v_and_b32_e32 v209, 0xffff0000, v68
	v_and_b32_e32 v192, 0xffff0000, v80
	v_and_b32_e32 v193, 0xffff0000, v92
	v_add_f32_e32 v193, v193, v192
	v_fma_f32 v192, v193, 0.5, -v209
	v_fmac_f32_e32 v209, v33, v192
	v_lshlrev_b32_e32 v210, 16, v69
	v_lshlrev_b32_e32 v192, 16, v81
	v_lshlrev_b32_e32 v193, 16, v93
	v_add_f32_e32 v193, v193, v192
	v_fma_f32 v192, v193, 0.5, -v210
	v_fmac_f32_e32 v210, v34, v192
	v_and_b32_e32 v211, 0xffff0000, v69
	v_and_b32_e32 v192, 0xffff0000, v81
	v_and_b32_e32 v193, 0xffff0000, v93
	v_add_f32_e32 v193, v193, v192
	v_fma_f32 v192, v193, 0.5, -v211
	v_fmac_f32_e32 v211, v35, v192
	v_lshlrev_b32_e32 v212, 16, v70
	v_lshlrev_b32_e32 v192, 16, v82
	v_lshlrev_b32_e32 v193, 16, v94
	v_add_f32_e32 v193, v193, v192
	v_fma_f32 v192, v193, 0.5, -v212
	v_fmac_f32_e32 v212, v36, v192
	v_and_b32_e32 v213, 0xffff0000, v70
	v_and_b32_e32 v192, 0xffff0000, v82
	v_and_b32_e32 v193, 0xffff0000, v94
	v_add_f32_e32 v193, v193, v192
	v_fma_f32 v192, v193, 0.5, -v213
	v_fmac_f32_e32 v213, v37, v192
	v_lshlrev_b32_e32 v214, 16, v71
	v_lshlrev_b32_e32 v192, 16, v83
	v_lshlrev_b32_e32 v193, 16, v95
	v_add_f32_e32 v193, v193, v192
	v_fma_f32 v192, v193, 0.5, -v214
	v_fmac_f32_e32 v214, v38, v192
	v_and_b32_e32 v215, 0xffff0000, v71
	v_and_b32_e32 v192, 0xffff0000, v83
	v_and_b32_e32 v193, 0xffff0000, v95
	v_add_f32_e32 v193, v193, v192
	v_fma_f32 v192, v193, 0.5, -v215
	v_fmac_f32_e32 v215, v39, v192
	v_lshlrev_b32_e32 v152, 16, v72
	v_lshlrev_b32_e32 v192, 16, v84
	v_lshlrev_b32_e32 v193, 16, v96
	v_add_f32_e32 v193, v193, v192
	v_fma_f32 v192, v193, 0.5, -v152
	v_fmac_f32_e32 v152, v40, v192
	v_and_b32_e32 v153, 0xffff0000, v72
	v_and_b32_e32 v192, 0xffff0000, v84
	v_and_b32_e32 v193, 0xffff0000, v96
	v_add_f32_e32 v193, v193, v192
	v_fma_f32 v192, v193, 0.5, -v153
	v_fmac_f32_e32 v153, v41, v192
	v_lshlrev_b32_e32 v154, 16, v73
	v_lshlrev_b32_e32 v192, 16, v85
	v_lshlrev_b32_e32 v193, 16, v97
	v_add_f32_e32 v193, v193, v192
	v_fma_f32 v192, v193, 0.5, -v154
	v_fmac_f32_e32 v154, v42, v192
	v_and_b32_e32 v155, 0xffff0000, v73
	v_and_b32_e32 v192, 0xffff0000, v85
	v_and_b32_e32 v193, 0xffff0000, v97
	v_add_f32_e32 v193, v193, v192
	v_fma_f32 v192, v193, 0.5, -v155
	v_fmac_f32_e32 v155, v43, v192
	v_lshlrev_b32_e32 v156, 16, v74
	v_lshlrev_b32_e32 v192, 16, v86
	v_lshlrev_b32_e32 v193, 16, v98
	v_add_f32_e32 v193, v193, v192
	v_fma_f32 v192, v193, 0.5, -v156
	v_fmac_f32_e32 v156, v44, v192
	v_and_b32_e32 v157, 0xffff0000, v74
	v_and_b32_e32 v192, 0xffff0000, v86
	v_and_b32_e32 v193, 0xffff0000, v98
	v_add_f32_e32 v193, v193, v192
	v_fma_f32 v192, v193, 0.5, -v157
	v_fmac_f32_e32 v157, v45, v192
	v_lshlrev_b32_e32 v158, 16, v75
	v_lshlrev_b32_e32 v192, 16, v87
	v_lshlrev_b32_e32 v193, 16, v99
	v_add_f32_e32 v193, v193, v192
	v_fma_f32 v192, v193, 0.5, -v158
	v_fmac_f32_e32 v158, v46, v192
	v_and_b32_e32 v159, 0xffff0000, v75
	v_and_b32_e32 v192, 0xffff0000, v87
	v_and_b32_e32 v193, 0xffff0000, v99
	v_add_f32_e32 v193, v193, v192
	v_fma_f32 v192, v193, 0.5, -v159
	v_fmac_f32_e32 v159, v47, v192
	v_add_u32_e32 v57, v59, v56
	v_add_u32_e32 v57, v59, v57
	v_cmp_lt_i32_e64 s[10:11], 0, v57
	v_cmp_gt_i32_e64 s[12:13], v58, v57
	v_mad_u32_u24 v205, v57, v53, v52
	s_nop 0
	v_cndmask_b32_e64 v206, 0, v53, s[10:11]
	v_cndmask_b32_e64 v207, 0, v53, s[12:13]
	v_cndmask_b32_e64 v60, 0, 1.0, s[10:11]
	v_cndmask_b32_e64 v61, 0, 1.0, s[12:13]
	v_sub_u32_e32 v206, v205, v206
	v_add_u32_e32 v207, v205, v207
	global_load_dwordx4 v[64:67], v205, s[72:73] offset:-2048
	global_load_dwordx4 v[68:71], v205, s[72:73]
	global_load_dwordx4 v[72:75], v205, s[72:73] offset:2048
	global_load_dwordx4 v[76:79], v206, s[72:73] offset:-2048
	global_load_dwordx4 v[80:83], v206, s[72:73]
	global_load_dwordx4 v[84:87], v206, s[72:73] offset:2048
	global_load_dwordx4 v[88:91], v207, s[72:73] offset:-2048
	global_load_dwordx4 v[92:95], v207, s[72:73]
	global_load_dwordx4 v[96:99], v207, s[72:73] offset:2048
	v_mul_f32_e32 v160, v0, v208
	v_mul_f32_e32 v161, v1, v209
	v_mul_f32_e32 v162, v2, v210
	v_mul_f32_e32 v163, v3, v211
	v_mul_f32_e32 v164, v4, v212
	v_mul_f32_e32 v165, v5, v213
	v_mul_f32_e32 v166, v6, v214
	v_mul_f32_e32 v167, v7, v215
	v_mul_f32_e32 v200, v160, v160
	v_fmac_f32_e32 v200, v161, v161
	v_fmac_f32_e32 v200, v162, v162
	v_fmac_f32_e32 v200, v163, v163
	v_fmac_f32_e32 v200, v164, v164
	v_fmac_f32_e32 v200, v165, v165
	v_fmac_f32_e32 v200, v166, v166
	v_fmac_f32_e32 v200, v167, v167
	s_waitcnt lgkmcnt(0)
	v_add_f32_e32 v192, -1.0, v184
	v_fma_f32 v192, v8, v192, 1.0
	v_mul_f32_e32 v176, v208, v192
	v_add_f32_dpp v200, v200, v200 quad_perm:[1,0,3,2] row_mask:0xf bank_mask:0xf bound_ctrl:1
	v_add_f32_e32 v192, -1.0, v185
	v_fma_f32 v192, v9, v192, 1.0
	v_mul_f32_e32 v177, v209, v192
	v_add_f32_dpp v200, v200, v200 quad_perm:[2,3,0,1] row_mask:0xf bank_mask:0xf bound_ctrl:1
	v_add_f32_e32 v192, -1.0, v186
	v_fma_f32 v192, v10, v192, 1.0
	v_mul_f32_e32 v178, v210, v192
	v_add_f32_dpp v200, v200, v200 row_half_mirror row_mask:0xf bank_mask:0xf bound_ctrl:1
	v_add_f32_e32 v192, -1.0, v187
	v_fma_f32 v192, v11, v192, 1.0
	v_mul_f32_e32 v179, v211, v192
	v_add_f32_e32 v192, -1.0, v188
	v_fma_f32 v192, v12, v192, 1.0
	v_mul_f32_e32 v180, v212, v192
	v_add_f32_e32 v192, -1.0, v189
	v_fma_f32 v192, v13, v192, 1.0
	v_mul_f32_e32 v181, v213, v192
	v_add_f32_e32 v192, -1.0, v190
	v_fma_f32 v192, v14, v192, 1.0
	v_mul_f32_e32 v182, v214, v192
	v_add_f32_e32 v192, -1.0, v191
	v_fma_f32 v192, v15, v192, 1.0
	v_mul_f32_e32 v183, v215, v192
	v_max_f32_e32 v200, 0x179abe15, v200
	v_rsq_f32_e32 v201, v200
	v_mul_f32_e32 v192, v136, v176
	v_mul_f32_e32 v202, v16, v192
	v_mul_f32_e32 v160, v160, v201
	v_mul_f32_e32 v161, v161, v201
	v_mul_f32_e32 v162, v162, v201
	v_mul_f32_e32 v163, v163, v201
	v_mul_f32_e32 v164, v164, v201
	v_mul_f32_e32 v165, v165, v201
	v_mul_f32_e32 v166, v166, v201
	v_mul_f32_e32 v167, v167, v201
	v_mul_f32_e32 v168, v184, v160
	v_mul_f32_e32 v169, v185, v161
	v_mul_f32_e32 v170, v186, v162
	v_mul_f32_e32 v171, v187, v163
	v_mul_f32_e32 v172, v188, v164
	v_mul_f32_e32 v173, v189, v165
	v_mul_f32_e32 v174, v190, v166
	v_mul_f32_e32 v175, v191, v167
	ds_write_b128 v54, v[160:163] offset:0
	ds_write_b128 v54, v[164:167] offset:16
	ds_write_b128 v54, v[168:171] offset:256
	ds_write_b128 v54, v[172:175] offset:272
	v_mul_f32_e32 v192, v137, v177
	v_fmac_f32_e32 v202, v17, v192
	v_mul_f32_e32 v192, v138, v178
	v_fmac_f32_e32 v202, v18, v192
	v_mul_f32_e32 v192, v139, v179
	v_fmac_f32_e32 v202, v19, v192
	v_mul_f32_e32 v192, v140, v180
	v_fmac_f32_e32 v202, v20, v192
	v_mul_f32_e32 v192, v141, v181
	v_fmac_f32_e32 v202, v21, v192
	v_mul_f32_e32 v192, v142, v182
	v_fmac_f32_e32 v202, v22, v192
	v_mul_f32_e32 v192, v143, v183
	v_fmac_f32_e32 v202, v23, v192
	ds_write_b128 v54, v[176:179] offset:512
	ds_write_b128 v54, v[180:183] offset:528
	v_add_f32_dpp v202, v202, v202 quad_perm:[1,0,3,2] row_mask:0xf bank_mask:0xf bound_ctrl:1
	ds_write_b128 v54, v[136:139] offset:768
	ds_write_b128 v54, v[140:143] offset:784
	v_add_f32_dpp v202, v202, v202 quad_perm:[2,3,0,1] row_mask:0xf bank_mask:0xf bound_ctrl:1
	ds_write_b128 v54, v[152:155] offset:1024
	ds_write_b128 v54, v[156:159] offset:1040
	v_add_f32_dpp v202, v202, v202 row_half_mirror row_mask:0xf bank_mask:0xf bound_ctrl:1
	v_lshl_add_u32 v205, v56, 7, s60
	s_and_saveexec_b64 s[6:7], s[8:9]
	global_store_dword v205, v202, s[24:25]
	s_or_b64 exec, exec, s[6:7]
	v_add_u32_e32 v56, v59, v56
	s_waitcnt lgkmcnt(0)
	s_barrier
	ds_read_b128 v[184:187], v55 offset:4096
	ds_read_b128 v[188:191], v55 offset:4112
	s_waitcnt vmcnt(9)
	v_lshlrev_b32_e32 v136, 16, v100
	v_lshlrev_b32_e32 v192, 16, v112
	v_lshlrev_b32_e32 v193, 16, v124
	v_add_f32_e32 v193, v193, v192
	v_fma_f32 v192, v193, 0.5, -v136
	v_fmac_f32_e32 v136, v24, v192
	v_and_b32_e32 v137, 0xffff0000, v100
	v_and_b32_e32 v192, 0xffff0000, v112
	v_and_b32_e32 v193, 0xffff0000, v124
	v_add_f32_e32 v193, v193, v192
	v_fma_f32 v192, v193, 0.5, -v137
	v_fmac_f32_e32 v137, v25, v192
	v_lshlrev_b32_e32 v138, 16, v101
	v_lshlrev_b32_e32 v192, 16, v113
	v_lshlrev_b32_e32 v193, 16, v125
	v_add_f32_e32 v193, v193, v192
	v_fma_f32 v192, v193, 0.5, -v138
	v_fmac_f32_e32 v138, v26, v192
	v_and_b32_e32 v139, 0xffff0000, v101
	v_and_b32_e32 v192, 0xffff0000, v113
	v_and_b32_e32 v193, 0xffff0000, v125
	v_add_f32_e32 v193, v193, v192
	v_fma_f32 v192, v193, 0.5, -v139
	v_fmac_f32_e32 v139, v27, v192
	v_lshlrev_b32_e32 v140, 16, v102
	v_lshlrev_b32_e32 v192, 16, v114
	v_lshlrev_b32_e32 v193, 16, v126
	v_add_f32_e32 v193, v193, v192
	v_fma_f32 v192, v193, 0.5, -v140
	v_fmac_f32_e32 v140, v28, v192
	v_and_b32_e32 v141, 0xffff0000, v102
	v_and_b32_e32 v192, 0xffff0000, v114
	v_and_b32_e32 v193, 0xffff0000, v126
	v_add_f32_e32 v193, v193, v192
	v_fma_f32 v192, v193, 0.5, -v141
	v_fmac_f32_e32 v141, v29, v192
	v_lshlrev_b32_e32 v142, 16, v103
	v_lshlrev_b32_e32 v192, 16, v115
	v_lshlrev_b32_e32 v193, 16, v127
	v_add_f32_e32 v193, v193, v192
	v_fma_f32 v192, v193, 0.5, -v142
	v_fmac_f32_e32 v142, v30, v192
	v_and_b32_e32 v143, 0xffff0000, v103
	v_and_b32_e32 v192, 0xffff0000, v115
	v_and_b32_e32 v193, 0xffff0000, v127
	v_add_f32_e32 v193, v193, v192
	v_fma_f32 v192, v193, 0.5, -v143
	v_fmac_f32_e32 v143, v31, v192
	v_lshlrev_b32_e32 v208, 16, v104
	v_lshlrev_b32_e32 v192, 16, v116
	v_lshlrev_b32_e32 v193, 16, v128
	v_add_f32_e32 v193, v193, v192
	v_fma_f32 v192, v193, 0.5, -v208
	v_fmac_f32_e32 v208, v32, v192
	v_and_b32_e32 v209, 0xffff0000, v104
	v_and_b32_e32 v192, 0xffff0000, v116
	v_and_b32_e32 v193, 0xffff0000, v128
	v_add_f32_e32 v193, v193, v192
	v_fma_f32 v192, v193, 0.5, -v209
	v_fmac_f32_e32 v209, v33, v192
	v_lshlrev_b32_e32 v210, 16, v105
	v_lshlrev_b32_e32 v192, 16, v117
	v_lshlrev_b32_e32 v193, 16, v129
	v_add_f32_e32 v193, v193, v192
	v_fma_f32 v192, v193, 0.5, -v210
	v_fmac_f32_e32 v210, v34, v192
	v_and_b32_e32 v211, 0xffff0000, v105
	v_and_b32_e32 v192, 0xffff0000, v117
	v_and_b32_e32 v193, 0xffff0000, v129
	v_add_f32_e32 v193, v193, v192
	v_fma_f32 v192, v193, 0.5, -v211
	v_fmac_f32_e32 v211, v35, v192
	v_lshlrev_b32_e32 v212, 16, v106
	v_lshlrev_b32_e32 v192, 16, v118
	v_lshlrev_b32_e32 v193, 16, v130
	v_add_f32_e32 v193, v193, v192
	v_fma_f32 v192, v193, 0.5, -v212
	v_fmac_f32_e32 v212, v36, v192
	v_and_b32_e32 v213, 0xffff0000, v106
	v_and_b32_e32 v192, 0xffff0000, v118
	v_and_b32_e32 v193, 0xffff0000, v130
	v_add_f32_e32 v193, v193, v192
	v_fma_f32 v192, v193, 0.5, -v213
	v_fmac_f32_e32 v213, v37, v192
	v_lshlrev_b32_e32 v214, 16, v107
	v_lshlrev_b32_e32 v192, 16, v119
	v_lshlrev_b32_e32 v193, 16, v131
	v_add_f32_e32 v193, v193, v192
	v_fma_f32 v192, v193, 0.5, -v214
	v_fmac_f32_e32 v214, v38, v192
	v_and_b32_e32 v215, 0xffff0000, v107
	v_and_b32_e32 v192, 0xffff0000, v119
	v_and_b32_e32 v193, 0xffff0000, v131
	v_add_f32_e32 v193, v193, v192
	v_fma_f32 v192, v193, 0.5, -v215
	v_fmac_f32_e32 v215, v39, v192
	v_lshlrev_b32_e32 v152, 16, v108
	v_lshlrev_b32_e32 v192, 16, v120
	v_lshlrev_b32_e32 v193, 16, v132
	v_add_f32_e32 v193, v193, v192
	v_fma_f32 v192, v193, 0.5, -v152
	v_fmac_f32_e32 v152, v40, v192
	v_and_b32_e32 v153, 0xffff0000, v108
	v_and_b32_e32 v192, 0xffff0000, v120
	v_and_b32_e32 v193, 0xffff0000, v132
	v_add_f32_e32 v193, v193, v192
	v_fma_f32 v192, v193, 0.5, -v153
	v_fmac_f32_e32 v153, v41, v192
	v_lshlrev_b32_e32 v154, 16, v109
	v_lshlrev_b32_e32 v192, 16, v121
	v_lshlrev_b32_e32 v193, 16, v133
	v_add_f32_e32 v193, v193, v192
	v_fma_f32 v192, v193, 0.5, -v154
	v_fmac_f32_e32 v154, v42, v192
	v_and_b32_e32 v155, 0xffff0000, v109
	v_and_b32_e32 v192, 0xffff0000, v121
	v_and_b32_e32 v193, 0xffff0000, v133
	v_add_f32_e32 v193, v193, v192
	v_fma_f32 v192, v193, 0.5, -v155
	v_fmac_f32_e32 v155, v43, v192
	v_lshlrev_b32_e32 v156, 16, v110
	v_lshlrev_b32_e32 v192, 16, v122
	v_lshlrev_b32_e32 v193, 16, v134
	v_add_f32_e32 v193, v193, v192
	v_fma_f32 v192, v193, 0.5, -v156
	v_fmac_f32_e32 v156, v44, v192
	v_and_b32_e32 v157, 0xffff0000, v110
	v_and_b32_e32 v192, 0xffff0000, v122
	v_and_b32_e32 v193, 0xffff0000, v134
	v_add_f32_e32 v193, v193, v192
	v_fma_f32 v192, v193, 0.5, -v157
	v_fmac_f32_e32 v157, v45, v192
	v_lshlrev_b32_e32 v158, 16, v111
	v_lshlrev_b32_e32 v192, 16, v123
	v_lshlrev_b32_e32 v193, 16, v135
	v_add_f32_e32 v193, v193, v192
	v_fma_f32 v192, v193, 0.5, -v158
	v_fmac_f32_e32 v158, v46, v192
	v_and_b32_e32 v159, 0xffff0000, v111
	v_and_b32_e32 v192, 0xffff0000, v123
	v_and_b32_e32 v193, 0xffff0000, v135
	v_add_f32_e32 v193, v193, v192
	v_fma_f32 v192, v193, 0.5, -v159
	v_fmac_f32_e32 v159, v47, v192
	v_add_u32_e32 v57, v59, v56
	v_add_u32_e32 v57, v59, v57
	v_cmp_lt_i32_e64 s[10:11], 0, v57
	v_cmp_gt_i32_e64 s[12:13], v58, v57
	v_mad_u32_u24 v205, v57, v53, v52
	s_nop 0
	v_cndmask_b32_e64 v206, 0, v53, s[10:11]
	v_cndmask_b32_e64 v207, 0, v53, s[12:13]
	v_cndmask_b32_e64 v62, 0, 1.0, s[10:11]
	v_cndmask_b32_e64 v63, 0, 1.0, s[12:13]
	v_sub_u32_e32 v206, v205, v206
	v_add_u32_e32 v207, v205, v207
	global_load_dwordx4 v[100:103], v205, s[72:73] offset:-2048
	global_load_dwordx4 v[104:107], v205, s[72:73]
	global_load_dwordx4 v[108:111], v205, s[72:73] offset:2048
	global_load_dwordx4 v[112:115], v206, s[72:73] offset:-2048
	global_load_dwordx4 v[116:119], v206, s[72:73]
	global_load_dwordx4 v[120:123], v206, s[72:73] offset:2048
	global_load_dwordx4 v[124:127], v207, s[72:73] offset:-2048
	global_load_dwordx4 v[128:131], v207, s[72:73]
	global_load_dwordx4 v[132:135], v207, s[72:73] offset:2048
	v_mul_f32_e32 v160, v0, v208
	v_mul_f32_e32 v161, v1, v209
	v_mul_f32_e32 v162, v2, v210
	v_mul_f32_e32 v163, v3, v211
	v_mul_f32_e32 v164, v4, v212
	v_mul_f32_e32 v165, v5, v213
	v_mul_f32_e32 v166, v6, v214
	v_mul_f32_e32 v167, v7, v215
	v_mul_f32_e32 v200, v160, v160
	v_fmac_f32_e32 v200, v161, v161
	v_fmac_f32_e32 v200, v162, v162
	v_fmac_f32_e32 v200, v163, v163
	v_fmac_f32_e32 v200, v164, v164
	v_fmac_f32_e32 v200, v165, v165
	v_fmac_f32_e32 v200, v166, v166
	v_fmac_f32_e32 v200, v167, v167
	s_waitcnt lgkmcnt(0)
	v_add_f32_e32 v192, -1.0, v184
	v_fma_f32 v192, v8, v192, 1.0
	v_mul_f32_e32 v176, v208, v192
	v_add_f32_dpp v200, v200, v200 quad_perm:[1,0,3,2] row_mask:0xf bank_mask:0xf bound_ctrl:1
	v_add_f32_e32 v192, -1.0, v185
	v_fma_f32 v192, v9, v192, 1.0
	v_mul_f32_e32 v177, v209, v192
	v_add_f32_dpp v200, v200, v200 quad_perm:[2,3,0,1] row_mask:0xf bank_mask:0xf bound_ctrl:1
	v_add_f32_e32 v192, -1.0, v186
	v_fma_f32 v192, v10, v192, 1.0
	v_mul_f32_e32 v178, v210, v192
	v_add_f32_dpp v200, v200, v200 row_half_mirror row_mask:0xf bank_mask:0xf bound_ctrl:1
	v_add_f32_e32 v192, -1.0, v187
	v_fma_f32 v192, v11, v192, 1.0
	v_mul_f32_e32 v179, v211, v192
	v_add_f32_e32 v192, -1.0, v188
	v_fma_f32 v192, v12, v192, 1.0
	v_mul_f32_e32 v180, v212, v192
	v_add_f32_e32 v192, -1.0, v189
	v_fma_f32 v192, v13, v192, 1.0
	v_mul_f32_e32 v181, v213, v192
	v_add_f32_e32 v192, -1.0, v190
	v_fma_f32 v192, v14, v192, 1.0
	v_mul_f32_e32 v182, v214, v192
	v_add_f32_e32 v192, -1.0, v191
	v_fma_f32 v192, v15, v192, 1.0
	v_mul_f32_e32 v183, v215, v192
	v_max_f32_e32 v200, 0x179abe15, v200
	v_rsq_f32_e32 v201, v200
	v_mul_f32_e32 v192, v136, v176
	v_mul_f32_e32 v202, v16, v192
	v_mul_f32_e32 v160, v160, v201
	v_mul_f32_e32 v161, v161, v201
	v_mul_f32_e32 v162, v162, v201
	v_mul_f32_e32 v163, v163, v201
	v_mul_f32_e32 v164, v164, v201
	v_mul_f32_e32 v165, v165, v201
	v_mul_f32_e32 v166, v166, v201
	v_mul_f32_e32 v167, v167, v201
	v_mul_f32_e32 v168, v184, v160
	v_mul_f32_e32 v169, v185, v161
	v_mul_f32_e32 v170, v186, v162
	v_mul_f32_e32 v171, v187, v163
	v_mul_f32_e32 v172, v188, v164
	v_mul_f32_e32 v173, v189, v165
	v_mul_f32_e32 v174, v190, v166
	v_mul_f32_e32 v175, v191, v167
	ds_write_b128 v54, v[160:163] offset:20480
	ds_write_b128 v54, v[164:167] offset:20496
	ds_write_b128 v54, v[168:171] offset:20736
	ds_write_b128 v54, v[172:175] offset:20752
	v_mul_f32_e32 v192, v137, v177
	v_fmac_f32_e32 v202, v17, v192
	v_mul_f32_e32 v192, v138, v178
	v_fmac_f32_e32 v202, v18, v192
	v_mul_f32_e32 v192, v139, v179
	v_fmac_f32_e32 v202, v19, v192
	v_mul_f32_e32 v192, v140, v180
	v_fmac_f32_e32 v202, v20, v192
	v_mul_f32_e32 v192, v141, v181
	v_fmac_f32_e32 v202, v21, v192
	v_mul_f32_e32 v192, v142, v182
	v_fmac_f32_e32 v202, v22, v192
	v_mul_f32_e32 v192, v143, v183
	v_fmac_f32_e32 v202, v23, v192
	ds_write_b128 v54, v[176:179] offset:20992
	ds_write_b128 v54, v[180:183] offset:21008
	v_add_f32_dpp v202, v202, v202 quad_perm:[1,0,3,2] row_mask:0xf bank_mask:0xf bound_ctrl:1
	ds_write_b128 v54, v[136:139] offset:21248
	ds_write_b128 v54, v[140:143] offset:21264
	v_add_f32_dpp v202, v202, v202 quad_perm:[2,3,0,1] row_mask:0xf bank_mask:0xf bound_ctrl:1
	ds_write_b128 v54, v[152:155] offset:21504
	ds_write_b128 v54, v[156:159] offset:21520
	v_add_f32_dpp v202, v202, v202 row_half_mirror row_mask:0xf bank_mask:0xf bound_ctrl:1
	v_lshl_add_u32 v205, v56, 7, s60
	s_and_saveexec_b64 s[6:7], s[8:9]
	global_store_dword v205, v202, s[24:25]
	s_or_b64 exec, exec, s[6:7]
	v_add_u32_e32 v56, v59, v56
	s_waitcnt lgkmcnt(0)
	s_barrier
	s_add_i32 s66, s66, 2
	s_cmp_lt_u32 s66, 1023
	s_cbranch_scc1 .Lmy_kp_loop
	ds_read_b128 v[184:187], v55 offset:0
	ds_read_b128 v[188:191], v55 offset:16
	s_waitcnt vmcnt(9)
	v_lshlrev_b32_e32 v136, 16, v64
	v_lshlrev_b32_e32 v192, 16, v76
	v_lshlrev_b32_e32 v193, 16, v88
	v_mul_f32_e32 v193, v61, v193
	v_fmac_f32_e32 v193, v60, v192
	v_fma_f32 v192, v193, 0.5, -v136
	v_fmac_f32_e32 v136, v24, v192
	v_and_b32_e32 v137, 0xffff0000, v64
	v_and_b32_e32 v192, 0xffff0000, v76
	v_and_b32_e32 v193, 0xffff0000, v88
	v_mul_f32_e32 v193, v61, v193
	v_fmac_f32_e32 v193, v60, v192
	v_fma_f32 v192, v193, 0.5, -v137
	v_fmac_f32_e32 v137, v25, v192
	v_lshlrev_b32_e32 v138, 16, v65
	v_lshlrev_b32_e32 v192, 16, v77
	v_lshlrev_b32_e32 v193, 16, v89
	v_mul_f32_e32 v193, v61, v193
	v_fmac_f32_e32 v193, v60, v192
	v_fma_f32 v192, v193, 0.5, -v138
	v_fmac_f32_e32 v138, v26, v192
	v_and_b32_e32 v139, 0xffff0000, v65
	v_and_b32_e32 v192, 0xffff0000, v77
	v_and_b32_e32 v193, 0xffff0000, v89
	v_mul_f32_e32 v193, v61, v193
	v_fmac_f32_e32 v193, v60, v192
	v_fma_f32 v192, v193, 0.5, -v139
	v_fmac_f32_e32 v139, v27, v192
	v_lshlrev_b32_e32 v140, 16, v66
	v_lshlrev_b32_e32 v192, 16, v78
	v_lshlrev_b32_e32 v193, 16, v90
	v_mul_f32_e32 v193, v61, v193
	v_fmac_f32_e32 v193, v60, v192
	v_fma_f32 v192, v193, 0.5, -v140
	v_fmac_f32_e32 v140, v28, v192
	v_and_b32_e32 v141, 0xffff0000, v66
	v_and_b32_e32 v192, 0xffff0000, v78
	v_and_b32_e32 v193, 0xffff0000, v90
	v_mul_f32_e32 v193, v61, v193
	v_fmac_f32_e32 v193, v60, v192
	v_fma_f32 v192, v193, 0.5, -v141
	v_fmac_f32_e32 v141, v29, v192
	v_lshlrev_b32_e32 v142, 16, v67
	v_lshlrev_b32_e32 v192, 16, v79
	v_lshlrev_b32_e32 v193, 16, v91
	v_mul_f32_e32 v193, v61, v193
	v_fmac_f32_e32 v193, v60, v192
	v_fma_f32 v192, v193, 0.5, -v142
	v_fmac_f32_e32 v142, v30, v192
	v_and_b32_e32 v143, 0xffff0000, v67
	v_and_b32_e32 v192, 0xffff0000, v79
	v_and_b32_e32 v193, 0xffff0000, v91
	v_mul_f32_e32 v193, v61, v193
	v_fmac_f32_e32 v193, v60, v192
	v_fma_f32 v192, v193, 0.5, -v143
	v_fmac_f32_e32 v143, v31, v192
	v_lshlrev_b32_e32 v208, 16, v68
	v_lshlrev_b32_e32 v192, 16, v80
	v_lshlrev_b32_e32 v193, 16, v92
	v_mul_f32_e32 v193, v61, v193
	v_fmac_f32_e32 v193, v60, v192
	v_fma_f32 v192, v193, 0.5, -v208
	v_fmac_f32_e32 v208, v32, v192
	v_and_b32_e32 v209, 0xffff0000, v68
	v_and_b32_e32 v192, 0xffff0000, v80
	v_and_b32_e32 v193, 0xffff0000, v92
	v_mul_f32_e32 v193, v61, v193
	v_fmac_f32_e32 v193, v60, v192
	v_fma_f32 v192, v193, 0.5, -v209
	v_fmac_f32_e32 v209, v33, v192
	v_lshlrev_b32_e32 v210, 16, v69
	v_lshlrev_b32_e32 v192, 16, v81
	v_lshlrev_b32_e32 v193, 16, v93
	v_mul_f32_e32 v193, v61, v193
	v_fmac_f32_e32 v193, v60, v192
	v_fma_f32 v192, v193, 0.5, -v210
	v_fmac_f32_e32 v210, v34, v192
	v_and_b32_e32 v211, 0xffff0000, v69
	v_and_b32_e32 v192, 0xffff0000, v81
	v_and_b32_e32 v193, 0xffff0000, v93
	v_mul_f32_e32 v193, v61, v193
	v_fmac_f32_e32 v193, v60, v192
	v_fma_f32 v192, v193, 0.5, -v211
	v_fmac_f32_e32 v211, v35, v192
	v_lshlrev_b32_e32 v212, 16, v70
	v_lshlrev_b32_e32 v192, 16, v82
	v_lshlrev_b32_e32 v193, 16, v94
	v_mul_f32_e32 v193, v61, v193
	v_fmac_f32_e32 v193, v60, v192
	v_fma_f32 v192, v193, 0.5, -v212
	v_fmac_f32_e32 v212, v36, v192
	v_and_b32_e32 v213, 0xffff0000, v70
	v_and_b32_e32 v192, 0xffff0000, v82
	v_and_b32_e32 v193, 0xffff0000, v94
	v_mul_f32_e32 v193, v61, v193
	v_fmac_f32_e32 v193, v60, v192
	v_fma_f32 v192, v193, 0.5, -v213
	v_fmac_f32_e32 v213, v37, v192
	v_lshlrev_b32_e32 v214, 16, v71
	v_lshlrev_b32_e32 v192, 16, v83
	v_lshlrev_b32_e32 v193, 16, v95
	v_mul_f32_e32 v193, v61, v193
	v_fmac_f32_e32 v193, v60, v192
	v_fma_f32 v192, v193, 0.5, -v214
	v_fmac_f32_e32 v214, v38, v192
	v_and_b32_e32 v215, 0xffff0000, v71
	v_and_b32_e32 v192, 0xffff0000, v83
	v_and_b32_e32 v193, 0xffff0000, v95
	v_mul_f32_e32 v193, v61, v193
	v_fmac_f32_e32 v193, v60, v192
	v_fma_f32 v192, v193, 0.5, -v215
	v_fmac_f32_e32 v215, v39, v192
	v_lshlrev_b32_e32 v152, 16, v72
	v_lshlrev_b32_e32 v192, 16, v84
	v_lshlrev_b32_e32 v193, 16, v96
	v_mul_f32_e32 v193, v61, v193
	v_fmac_f32_e32 v193, v60, v192
	v_fma_f32 v192, v193, 0.5, -v152
	v_fmac_f32_e32 v152, v40, v192
	v_and_b32_e32 v153, 0xffff0000, v72
	v_and_b32_e32 v192, 0xffff0000, v84
	v_and_b32_e32 v193, 0xffff0000, v96
	v_mul_f32_e32 v193, v61, v193
	v_fmac_f32_e32 v193, v60, v192
	v_fma_f32 v192, v193, 0.5, -v153
	v_fmac_f32_e32 v153, v41, v192
	v_lshlrev_b32_e32 v154, 16, v73
	v_lshlrev_b32_e32 v192, 16, v85
	v_lshlrev_b32_e32 v193, 16, v97
	v_mul_f32_e32 v193, v61, v193
	v_fmac_f32_e32 v193, v60, v192
	v_fma_f32 v192, v193, 0.5, -v154
	v_fmac_f32_e32 v154, v42, v192
	v_and_b32_e32 v155, 0xffff0000, v73
	v_and_b32_e32 v192, 0xffff0000, v85
	v_and_b32_e32 v193, 0xffff0000, v97
	v_mul_f32_e32 v193, v61, v193
	v_fmac_f32_e32 v193, v60, v192
	v_fma_f32 v192, v193, 0.5, -v155
	v_fmac_f32_e32 v155, v43, v192
	v_lshlrev_b32_e32 v156, 16, v74
	v_lshlrev_b32_e32 v192, 16, v86
	v_lshlrev_b32_e32 v193, 16, v98
	v_mul_f32_e32 v193, v61, v193
	v_fmac_f32_e32 v193, v60, v192
	v_fma_f32 v192, v193, 0.5, -v156
	v_fmac_f32_e32 v156, v44, v192
	v_and_b32_e32 v157, 0xffff0000, v74
	v_and_b32_e32 v192, 0xffff0000, v86
	v_and_b32_e32 v193, 0xffff0000, v98
	v_mul_f32_e32 v193, v61, v193
	v_fmac_f32_e32 v193, v60, v192
	v_fma_f32 v192, v193, 0.5, -v157
	v_fmac_f32_e32 v157, v45, v192
	v_lshlrev_b32_e32 v158, 16, v75
	v_lshlrev_b32_e32 v192, 16, v87
	v_lshlrev_b32_e32 v193, 16, v99
	v_mul_f32_e32 v193, v61, v193
	v_fmac_f32_e32 v193, v60, v192
	v_fma_f32 v192, v193, 0.5, -v158
	v_fmac_f32_e32 v158, v46, v192
	v_and_b32_e32 v159, 0xffff0000, v75
	v_and_b32_e32 v192, 0xffff0000, v87
	v_and_b32_e32 v193, 0xffff0000, v99
	v_mul_f32_e32 v193, v61, v193
	v_fmac_f32_e32 v193, v60, v192
	v_fma_f32 v192, v193, 0.5, -v159
	v_fmac_f32_e32 v159, v47, v192
	v_mul_f32_e32 v160, v0, v208
	v_mul_f32_e32 v161, v1, v209
	v_mul_f32_e32 v162, v2, v210
	v_mul_f32_e32 v163, v3, v211
	v_mul_f32_e32 v164, v4, v212
	v_mul_f32_e32 v165, v5, v213
	v_mul_f32_e32 v166, v6, v214
	v_mul_f32_e32 v167, v7, v215
	v_mul_f32_e32 v200, v160, v160
	v_fmac_f32_e32 v200, v161, v161
	v_fmac_f32_e32 v200, v162, v162
	v_fmac_f32_e32 v200, v163, v163
	v_fmac_f32_e32 v200, v164, v164
	v_fmac_f32_e32 v200, v165, v165
	v_fmac_f32_e32 v200, v166, v166
	v_fmac_f32_e32 v200, v167, v167
	s_waitcnt lgkmcnt(0)
	v_add_f32_e32 v192, -1.0, v184
	v_fma_f32 v192, v8, v192, 1.0
	v_mul_f32_e32 v176, v208, v192
	v_add_f32_dpp v200, v200, v200 quad_perm:[1,0,3,2] row_mask:0xf bank_mask:0xf bound_ctrl:1
	v_add_f32_e32 v192, -1.0, v185
	v_fma_f32 v192, v9, v192, 1.0
	v_mul_f32_e32 v177, v209, v192
	v_add_f32_dpp v200, v200, v200 quad_perm:[2,3,0,1] row_mask:0xf bank_mask:0xf bound_ctrl:1
	v_add_f32_e32 v192, -1.0, v186
	v_fma_f32 v192, v10, v192, 1.0
	v_mul_f32_e32 v178, v210, v192
	v_add_f32_dpp v200, v200, v200 row_half_mirror row_mask:0xf bank_mask:0xf bound_ctrl:1
	v_add_f32_e32 v192, -1.0, v187
	v_fma_f32 v192, v11, v192, 1.0
	v_mul_f32_e32 v179, v211, v192
	v_add_f32_e32 v192, -1.0, v188
	v_fma_f32 v192, v12, v192, 1.0
	v_mul_f32_e32 v180, v212, v192
	v_add_f32_e32 v192, -1.0, v189
	v_fma_f32 v192, v13, v192, 1.0
	v_mul_f32_e32 v181, v213, v192
	v_add_f32_e32 v192, -1.0, v190
	v_fma_f32 v192, v14, v192, 1.0
	v_mul_f32_e32 v182, v214, v192
	v_add_f32_e32 v192, -1.0, v191
	v_fma_f32 v192, v15, v192, 1.0
	v_mul_f32_e32 v183, v215, v192
	v_max_f32_e32 v200, 0x179abe15, v200
	v_rsq_f32_e32 v201, v200
	v_mul_f32_e32 v192, v136, v176
	v_mul_f32_e32 v202, v16, v192
	v_mul_f32_e32 v160, v160, v201
	v_mul_f32_e32 v161, v161, v201
	v_mul_f32_e32 v162, v162, v201
	v_mul_f32_e32 v163, v163, v201
	v_mul_f32_e32 v164, v164, v201
	v_mul_f32_e32 v165, v165, v201
	v_mul_f32_e32 v166, v166, v201
	v_mul_f32_e32 v167, v167, v201
	v_mul_f32_e32 v168, v184, v160
	v_mul_f32_e32 v169, v185, v161
	v_mul_f32_e32 v170, v186, v162
	v_mul_f32_e32 v171, v187, v163
	v_mul_f32_e32 v172, v188, v164
	v_mul_f32_e32 v173, v189, v165
	v_mul_f32_e32 v174, v190, v166
	v_mul_f32_e32 v175, v191, v167
	ds_write_b128 v54, v[160:163] offset:0
	ds_write_b128 v54, v[164:167] offset:16
	ds_write_b128 v54, v[168:171] offset:256
	ds_write_b128 v54, v[172:175] offset:272
	v_mul_f32_e32 v192, v137, v177
	v_fmac_f32_e32 v202, v17, v192
	v_mul_f32_e32 v192, v138, v178
	v_fmac_f32_e32 v202, v18, v192
	v_mul_f32_e32 v192, v139, v179
	v_fmac_f32_e32 v202, v19, v192
	v_mul_f32_e32 v192, v140, v180
	v_fmac_f32_e32 v202, v20, v192
	v_mul_f32_e32 v192, v141, v181
	v_fmac_f32_e32 v202, v21, v192
	v_mul_f32_e32 v192, v142, v182
	v_fmac_f32_e32 v202, v22, v192
	v_mul_f32_e32 v192, v143, v183
	v_fmac_f32_e32 v202, v23, v192
	ds_write_b128 v54, v[176:179] offset:512
	ds_write_b128 v54, v[180:183] offset:528
	v_add_f32_dpp v202, v202, v202 quad_perm:[1,0,3,2] row_mask:0xf bank_mask:0xf bound_ctrl:1
	ds_write_b128 v54, v[136:139] offset:768
	ds_write_b128 v54, v[140:143] offset:784
	v_add_f32_dpp v202, v202, v202 quad_perm:[2,3,0,1] row_mask:0xf bank_mask:0xf bound_ctrl:1
	ds_write_b128 v54, v[152:155] offset:1024
	ds_write_b128 v54, v[156:159] offset:1040
	v_add_f32_dpp v202, v202, v202 row_half_mirror row_mask:0xf bank_mask:0xf bound_ctrl:1
	v_lshl_add_u32 v205, v56, 7, s60
	s_and_saveexec_b64 s[6:7], s[8:9]
	global_store_dword v205, v202, s[24:25]
	s_or_b64 exec, exec, s[6:7]
	v_add_u32_e32 v56, v59, v56
	s_waitcnt lgkmcnt(0)
	s_barrier
	ds_read_b128 v[184:187], v55 offset:4096
	ds_read_b128 v[188:191], v55 offset:4112
	s_waitcnt vmcnt(0)
	v_lshlrev_b32_e32 v136, 16, v100
	v_lshlrev_b32_e32 v192, 16, v112
	v_lshlrev_b32_e32 v193, 16, v124
	v_mul_f32_e32 v193, v63, v193
	v_fmac_f32_e32 v193, v62, v192
	v_fma_f32 v192, v193, 0.5, -v136
	v_fmac_f32_e32 v136, v24, v192
	v_and_b32_e32 v137, 0xffff0000, v100
	v_and_b32_e32 v192, 0xffff0000, v112
	v_and_b32_e32 v193, 0xffff0000, v124
	v_mul_f32_e32 v193, v63, v193
	v_fmac_f32_e32 v193, v62, v192
	v_fma_f32 v192, v193, 0.5, -v137
	v_fmac_f32_e32 v137, v25, v192
	v_lshlrev_b32_e32 v138, 16, v101
	v_lshlrev_b32_e32 v192, 16, v113
	v_lshlrev_b32_e32 v193, 16, v125
	v_mul_f32_e32 v193, v63, v193
	v_fmac_f32_e32 v193, v62, v192
	v_fma_f32 v192, v193, 0.5, -v138
	v_fmac_f32_e32 v138, v26, v192
	v_and_b32_e32 v139, 0xffff0000, v101
	v_and_b32_e32 v192, 0xffff0000, v113
	v_and_b32_e32 v193, 0xffff0000, v125
	v_mul_f32_e32 v193, v63, v193
	v_fmac_f32_e32 v193, v62, v192
	v_fma_f32 v192, v193, 0.5, -v139
	v_fmac_f32_e32 v139, v27, v192
	v_lshlrev_b32_e32 v140, 16, v102
	v_lshlrev_b32_e32 v192, 16, v114
	v_lshlrev_b32_e32 v193, 16, v126
	v_mul_f32_e32 v193, v63, v193
	v_fmac_f32_e32 v193, v62, v192
	v_fma_f32 v192, v193, 0.5, -v140
	v_fmac_f32_e32 v140, v28, v192
	v_and_b32_e32 v141, 0xffff0000, v102
	v_and_b32_e32 v192, 0xffff0000, v114
	v_and_b32_e32 v193, 0xffff0000, v126
	v_mul_f32_e32 v193, v63, v193
	v_fmac_f32_e32 v193, v62, v192
	v_fma_f32 v192, v193, 0.5, -v141
	v_fmac_f32_e32 v141, v29, v192
	v_lshlrev_b32_e32 v142, 16, v103
	v_lshlrev_b32_e32 v192, 16, v115
	v_lshlrev_b32_e32 v193, 16, v127
	v_mul_f32_e32 v193, v63, v193
	v_fmac_f32_e32 v193, v62, v192
	v_fma_f32 v192, v193, 0.5, -v142
	v_fmac_f32_e32 v142, v30, v192
	v_and_b32_e32 v143, 0xffff0000, v103
	v_and_b32_e32 v192, 0xffff0000, v115
	v_and_b32_e32 v193, 0xffff0000, v127
	v_mul_f32_e32 v193, v63, v193
	v_fmac_f32_e32 v193, v62, v192
	v_fma_f32 v192, v193, 0.5, -v143
	v_fmac_f32_e32 v143, v31, v192
	v_lshlrev_b32_e32 v208, 16, v104
	v_lshlrev_b32_e32 v192, 16, v116
	v_lshlrev_b32_e32 v193, 16, v128
	v_mul_f32_e32 v193, v63, v193
	v_fmac_f32_e32 v193, v62, v192
	v_fma_f32 v192, v193, 0.5, -v208
	v_fmac_f32_e32 v208, v32, v192
	v_and_b32_e32 v209, 0xffff0000, v104
	v_and_b32_e32 v192, 0xffff0000, v116
	v_and_b32_e32 v193, 0xffff0000, v128
	v_mul_f32_e32 v193, v63, v193
	v_fmac_f32_e32 v193, v62, v192
	v_fma_f32 v192, v193, 0.5, -v209
	v_fmac_f32_e32 v209, v33, v192
	v_lshlrev_b32_e32 v210, 16, v105
	v_lshlrev_b32_e32 v192, 16, v117
	v_lshlrev_b32_e32 v193, 16, v129
	v_mul_f32_e32 v193, v63, v193
	v_fmac_f32_e32 v193, v62, v192
	v_fma_f32 v192, v193, 0.5, -v210
	v_fmac_f32_e32 v210, v34, v192
	v_and_b32_e32 v211, 0xffff0000, v105
	v_and_b32_e32 v192, 0xffff0000, v117
	v_and_b32_e32 v193, 0xffff0000, v129
	v_mul_f32_e32 v193, v63, v193
	v_fmac_f32_e32 v193, v62, v192
	v_fma_f32 v192, v193, 0.5, -v211
	v_fmac_f32_e32 v211, v35, v192
	v_lshlrev_b32_e32 v212, 16, v106
	v_lshlrev_b32_e32 v192, 16, v118
	v_lshlrev_b32_e32 v193, 16, v130
	v_mul_f32_e32 v193, v63, v193
	v_fmac_f32_e32 v193, v62, v192
	v_fma_f32 v192, v193, 0.5, -v212
	v_fmac_f32_e32 v212, v36, v192
	v_and_b32_e32 v213, 0xffff0000, v106
	v_and_b32_e32 v192, 0xffff0000, v118
	v_and_b32_e32 v193, 0xffff0000, v130
	v_mul_f32_e32 v193, v63, v193
	v_fmac_f32_e32 v193, v62, v192
	v_fma_f32 v192, v193, 0.5, -v213
	v_fmac_f32_e32 v213, v37, v192
	v_lshlrev_b32_e32 v214, 16, v107
	v_lshlrev_b32_e32 v192, 16, v119
	v_lshlrev_b32_e32 v193, 16, v131
	v_mul_f32_e32 v193, v63, v193
	v_fmac_f32_e32 v193, v62, v192
	v_fma_f32 v192, v193, 0.5, -v214
	v_fmac_f32_e32 v214, v38, v192
	v_and_b32_e32 v215, 0xffff0000, v107
	v_and_b32_e32 v192, 0xffff0000, v119
	v_and_b32_e32 v193, 0xffff0000, v131
	v_mul_f32_e32 v193, v63, v193
	v_fmac_f32_e32 v193, v62, v192
	v_fma_f32 v192, v193, 0.5, -v215
	v_fmac_f32_e32 v215, v39, v192
	v_lshlrev_b32_e32 v152, 16, v108
	v_lshlrev_b32_e32 v192, 16, v120
	v_lshlrev_b32_e32 v193, 16, v132
	v_mul_f32_e32 v193, v63, v193
	v_fmac_f32_e32 v193, v62, v192
	v_fma_f32 v192, v193, 0.5, -v152
	v_fmac_f32_e32 v152, v40, v192
	v_and_b32_e32 v153, 0xffff0000, v108
	v_and_b32_e32 v192, 0xffff0000, v120
	v_and_b32_e32 v193, 0xffff0000, v132
	v_mul_f32_e32 v193, v63, v193
	v_fmac_f32_e32 v193, v62, v192
	v_fma_f32 v192, v193, 0.5, -v153
	v_fmac_f32_e32 v153, v41, v192
	v_lshlrev_b32_e32 v154, 16, v109
	v_lshlrev_b32_e32 v192, 16, v121
	v_lshlrev_b32_e32 v193, 16, v133
	v_mul_f32_e32 v193, v63, v193
	v_fmac_f32_e32 v193, v62, v192
	v_fma_f32 v192, v193, 0.5, -v154
	v_fmac_f32_e32 v154, v42, v192
	v_and_b32_e32 v155, 0xffff0000, v109
	v_and_b32_e32 v192, 0xffff0000, v121
	v_and_b32_e32 v193, 0xffff0000, v133
	v_mul_f32_e32 v193, v63, v193
	v_fmac_f32_e32 v193, v62, v192
	v_fma_f32 v192, v193, 0.5, -v155
	v_fmac_f32_e32 v155, v43, v192
	v_lshlrev_b32_e32 v156, 16, v110
	v_lshlrev_b32_e32 v192, 16, v122
	v_lshlrev_b32_e32 v193, 16, v134
	v_mul_f32_e32 v193, v63, v193
	v_fmac_f32_e32 v193, v62, v192
	v_fma_f32 v192, v193, 0.5, -v156
	v_fmac_f32_e32 v156, v44, v192
	v_and_b32_e32 v157, 0xffff0000, v110
	v_and_b32_e32 v192, 0xffff0000, v122
	v_and_b32_e32 v193, 0xffff0000, v134
	v_mul_f32_e32 v193, v63, v193
	v_fmac_f32_e32 v193, v62, v192
	v_fma_f32 v192, v193, 0.5, -v157
	v_fmac_f32_e32 v157, v45, v192
	v_lshlrev_b32_e32 v158, 16, v111
	v_lshlrev_b32_e32 v192, 16, v123
	v_lshlrev_b32_e32 v193, 16, v135
	v_mul_f32_e32 v193, v63, v193
	v_fmac_f32_e32 v193, v62, v192
	v_fma_f32 v192, v193, 0.5, -v158
	v_fmac_f32_e32 v158, v46, v192
	v_and_b32_e32 v159, 0xffff0000, v111
	v_and_b32_e32 v192, 0xffff0000, v123
	v_and_b32_e32 v193, 0xffff0000, v135
	v_mul_f32_e32 v193, v63, v193
	v_fmac_f32_e32 v193, v62, v192
	v_fma_f32 v192, v193, 0.5, -v159
	v_fmac_f32_e32 v159, v47, v192
	v_mul_f32_e32 v160, v0, v208
	v_mul_f32_e32 v161, v1, v209
	v_mul_f32_e32 v162, v2, v210
	v_mul_f32_e32 v163, v3, v211
	v_mul_f32_e32 v164, v4, v212
	v_mul_f32_e32 v165, v5, v213
	v_mul_f32_e32 v166, v6, v214
	v_mul_f32_e32 v167, v7, v215
	v_mul_f32_e32 v200, v160, v160
	v_fmac_f32_e32 v200, v161, v161
	v_fmac_f32_e32 v200, v162, v162
	v_fmac_f32_e32 v200, v163, v163
	v_fmac_f32_e32 v200, v164, v164
	v_fmac_f32_e32 v200, v165, v165
	v_fmac_f32_e32 v200, v166, v166
	v_fmac_f32_e32 v200, v167, v167
	s_waitcnt lgkmcnt(0)
	v_add_f32_e32 v192, -1.0, v184
	v_fma_f32 v192, v8, v192, 1.0
	v_mul_f32_e32 v176, v208, v192
	v_add_f32_dpp v200, v200, v200 quad_perm:[1,0,3,2] row_mask:0xf bank_mask:0xf bound_ctrl:1
	v_add_f32_e32 v192, -1.0, v185
	v_fma_f32 v192, v9, v192, 1.0
	v_mul_f32_e32 v177, v209, v192
	v_add_f32_dpp v200, v200, v200 quad_perm:[2,3,0,1] row_mask:0xf bank_mask:0xf bound_ctrl:1
	v_add_f32_e32 v192, -1.0, v186
	v_fma_f32 v192, v10, v192, 1.0
	v_mul_f32_e32 v178, v210, v192
	v_add_f32_dpp v200, v200, v200 row_half_mirror row_mask:0xf bank_mask:0xf bound_ctrl:1
	v_add_f32_e32 v192, -1.0, v187
	v_fma_f32 v192, v11, v192, 1.0
	v_mul_f32_e32 v179, v211, v192
	v_add_f32_e32 v192, -1.0, v188
	v_fma_f32 v192, v12, v192, 1.0
	v_mul_f32_e32 v180, v212, v192
	v_add_f32_e32 v192, -1.0, v189
	v_fma_f32 v192, v13, v192, 1.0
	v_mul_f32_e32 v181, v213, v192
	v_add_f32_e32 v192, -1.0, v190
	v_fma_f32 v192, v14, v192, 1.0
	v_mul_f32_e32 v182, v214, v192
	v_add_f32_e32 v192, -1.0, v191
	v_fma_f32 v192, v15, v192, 1.0
	v_mul_f32_e32 v183, v215, v192
	v_max_f32_e32 v200, 0x179abe15, v200
	v_rsq_f32_e32 v201, v200
	v_mul_f32_e32 v192, v136, v176
	v_mul_f32_e32 v202, v16, v192
	v_mul_f32_e32 v160, v160, v201
	v_mul_f32_e32 v161, v161, v201
	v_mul_f32_e32 v162, v162, v201
	v_mul_f32_e32 v163, v163, v201
	v_mul_f32_e32 v164, v164, v201
	v_mul_f32_e32 v165, v165, v201
	v_mul_f32_e32 v166, v166, v201
	v_mul_f32_e32 v167, v167, v201
	v_mul_f32_e32 v168, v184, v160
	v_mul_f32_e32 v169, v185, v161
	v_mul_f32_e32 v170, v186, v162
	v_mul_f32_e32 v171, v187, v163
	v_mul_f32_e32 v172, v188, v164
	v_mul_f32_e32 v173, v189, v165
	v_mul_f32_e32 v174, v190, v166
	v_mul_f32_e32 v175, v191, v167
	ds_write_b128 v54, v[160:163] offset:20480
	ds_write_b128 v54, v[164:167] offset:20496
	ds_write_b128 v54, v[168:171] offset:20736
	ds_write_b128 v54, v[172:175] offset:20752
	v_mul_f32_e32 v192, v137, v177
	v_fmac_f32_e32 v202, v17, v192
	v_mul_f32_e32 v192, v138, v178
	v_fmac_f32_e32 v202, v18, v192
	v_mul_f32_e32 v192, v139, v179
	v_fmac_f32_e32 v202, v19, v192
	v_mul_f32_e32 v192, v140, v180
	v_fmac_f32_e32 v202, v20, v192
	v_mul_f32_e32 v192, v141, v181
	v_fmac_f32_e32 v202, v21, v192
	v_mul_f32_e32 v192, v142, v182
	v_fmac_f32_e32 v202, v22, v192
	v_mul_f32_e32 v192, v143, v183
	v_fmac_f32_e32 v202, v23, v192
	ds_write_b128 v54, v[176:179] offset:20992
	ds_write_b128 v54, v[180:183] offset:21008
	v_add_f32_dpp v202, v202, v202 quad_perm:[1,0,3,2] row_mask:0xf bank_mask:0xf bound_ctrl:1
	ds_write_b128 v54, v[136:139] offset:21248
	ds_write_b128 v54, v[140:143] offset:21264
	v_add_f32_dpp v202, v202, v202 quad_perm:[2,3,0,1] row_mask:0xf bank_mask:0xf bound_ctrl:1
	ds_write_b128 v54, v[152:155] offset:21504
	ds_write_b128 v54, v[156:159] offset:21520
	v_add_f32_dpp v202, v202, v202 row_half_mirror row_mask:0xf bank_mask:0xf bound_ctrl:1
	v_lshl_add_u32 v205, v56, 7, s60
	s_and_saveexec_b64 s[6:7], s[8:9]
	global_store_dword v205, v202, s[24:25]
	s_or_b64 exec, exec, s[6:7]
	v_add_u32_e32 v56, v59, v56
	s_waitcnt lgkmcnt(0)
	s_barrier
	s_waitcnt lgkmcnt(0)
	s_barrier
